# dn_seq: full-line stores by idle waves, gl table preload
# speedup vs baseline: 1.0150x; 1.0150x over previous
; __device__ __forceinline__ u32x2 pk4(f32x4 v) { u32x2 r; r.x = pk2(v[0], v[1]); r.y = pk2(v[2], v[3]); return r; }
; __device__ __forceinline__ f32x4 up4(u32x2 u) { return (f32x4){lo16(u.x), hi16(u.x), lo16(u.y), hi16(u.y)}; }
; __device__ __forceinline__ f32x4 mfma16(bf16x8 a, bf16x8 b, f32x4 c) { return __builtin_amdgcn_mfma_f32_16x16x32_bf16(a, b, c, 0, 0, 0); }
;     template <class Tp> __device__ __forceinline__ Tp* W(size_t off) const { return (Tp*)(ws + off); }
; __device__ __forceinline__ void dn_step(const DnStage& S, f32x4 (&Sacc)[2], bf16_t* ST, bf16_t* VN, bf16_t* dVnT, bf16_t* dST, int ck, int h, int vs, int wave, int r, int q) {
;     const size_t ch = (size_t)(ck * 8 + h);
;     if (wave < 4) {
;         bf16x8 sf[4];
; #pragma unroll
;         for (int kk = 0; kk < 4; ++kk) sf[kk] = *(const bf16x8*)(ST + r * 136 + kk * 32 + q * 8);
;         f32x4 a = (f32x4){0.f, 0.f, 0.f, 0.f};
; #pragma unroll
;         for (int kk = 0; kk < 4; ++kk) a = mfma16(S.f[kk], sf[kk], a);
;         const f32x4 vn = up4(S.u) - a; const u32x2 pv = pk4(vn);
;         *(u32x2*)(VN + r * 72 + wave * 16 + 4 * q) = pv;
;         *(u32x2*)(dVnT + (ch * 128 + vs * 16 + r) * 64 + wave * 16 + 4 * q) = pv;
;     }
;     asm volatile("s_waitcnt lgkmcnt(0)" ::: "memory"); __builtin_amdgcn_s_barrier(); asm volatile("" ::: "memory");
; __device__ void dn_seq(const Ctx& c, int h, int vs) {
;     const bf16_t* dW = c.W<bf16_t>(WS_DW); const bf16_t* dUT = c.W<bf16_t>(WS_DUT); const bf16_t* dKdT = c.W<bf16_t>(WS_DKDT); const float* dGl = c.W<float>(WS_DGL);
;     bf16_t* dVnT = c.W<bf16_t>(WS_DVNT); bf16_t* dST = c.W<bf16_t>(WS_DST);
;     bf16_t* ST = (bf16_t*)c.ldsf; bf16_t* VN = ST + 16 * 136;
;     const int wave = c.wave, r = c.r, q = c.q;
;     f32x4 Sacc[2]; Sacc[0] = (f32x4){0.f, 0.f, 0.f, 0.f}; Sacc[1] = Sacc[0];
;     __syncthreads();
;     { u32x2 z; z.x = 0u; z.y = 0u; *(u32x2*)(ST + r * 136 + wave * 16 + 4 * q) = z;
;       *(u32x2*)(dST + ((size_t)h * 128 + vs * 16 + r) * 128 + wave * 16 + 4 * q) = z; }
;     __syncthreads();
.LBB0_524:
	s_and_b64 vcc, exec, s[0:1]
	s_cbranch_vccz .LBB0_605
	s_load_dwordx2 s[4:5], s[94:95], 0xe8
	s_and_b32 s11, s92, 7
	s_lshr_b32 s12, s92, 3
	v_and_b32_e32 v1, 15, v234
	v_bfe_u32 v2, v234, 4, 2
	s_and_b32 s13, s22, 3
	s_waitcnt vmcnt(0) lgkmcnt(0)
	s_barrier
	v_mul_u32_u24_e32 v3, 0x110, v1
	v_lshl_add_u32 v4, v2, 3, v3
	s_lshl_b32 s0, s22, 5
	v_add_u32_e32 v4, s0, v4
	v_mov_b32_e32 v8, 0
	v_mov_b32_e32 v9, 0
	ds_write_b64 v4, v[8:9]
	s_lshl_b32 s1, s12, 4
	v_add_u32_e32 v5, s1, v1
	v_lshlrev_b32_e32 v6, 8, v5
	v_lshl_add_u32 v6, v2, 3, v6
	v_add_u32_e32 v7, s0, v6
	s_lshl_b32 s2, s11, 15
	s_add_u32 s6, s4, 0x27900000
	s_addc_u32 s7, s5, 0
	s_add_u32 s6, s6, s2
	s_addc_u32 s7, s7, 0
	s_waitcnt lgkmcnt(0)
	s_barrier
	s_lshl_b32 s3, s11, 14
	s_cmp_gt_u32 s22, 3
	s_cbranch_scc1 .Ldq_B
	s_lshl_b32 s0, s22, 4
	v_add_u32_e32 v10, s0, v1
	v_lshlrev_b32_e32 v10, 8, v10
	v_lshl_add_u32 v10, v2, 4, v10
	v_lshlrev_b32_e32 v11, 7, v5
	v_lshl_add_u32 v11, v2, 3, v11
	s_lshl_b32 s0, s22, 5
	v_add_u32_e32 v11, s0, v11
	v_lshl_add_u32 v12, v2, 4, v3
	v_mul_u32_u24_e32 v13, 0x90, v1
	v_lshl_add_u32 v13, v2, 3, v13
	v_add_u32_e32 v13, s0, v13
	v_add_u32_e32 v13, 0x1100, v13
	v_and_b32_e32 v0, 63, v234
	v_lshrrev_b32_e32 v14, 4, v0
	s_lshl_b32 s1, s22, 2
	v_add_u32_e32 v14, s1, v14
	v_and_b32_e32 v15, 15, v0
	v_mul_u32_u24_e32 v7, 0x110, v14
	v_lshl_add_u32 v7, v15, 4, v7
	v_mul_u32_u24_e32 v8, 0x90, v14
	v_lshl_add_u32 v8, v15, 3, v8
	v_add_u32_e32 v8, 0x1100, v8
	s_lshl_b32 s1, s12, 4
	v_add_u32_e32 v9, s1, v14
	v_lshlrev_b32_e32 v6, 8, v9
	v_lshl_add_u32 v6, v15, 4, v6
	v_lshlrev_b32_e32 v9, 7, v9
	v_lshl_add_u32 v9, v15, 3, v9
	s_add_u32 s14, s4, 0x22100000
	s_addc_u32 s15, s5, 0
	s_add_u32 s14, s14, s3
	s_addc_u32 s15, s15, 0
	s_add_u32 s16, s4, 0x23100000
	s_addc_u32 s17, s5, 0
	s_add_u32 s16, s16, s3
	s_addc_u32 s17, s17, 0
	s_add_u32 s18, s4, 0x26900000
	s_addc_u32 s19, s5, 0
	s_add_u32 s18, s18, s3
	s_addc_u32 s19, s19, 0
	global_load_dwordx4 v[16:19], v10, s[14:15] offset:0
	global_load_dwordx4 v[20:23], v10, s[14:15] offset:64
	global_load_dwordx4 v[24:27], v10, s[14:15] offset:128
	global_load_dwordx4 v[28:31], v10, s[14:15] offset:192
	global_load_dwordx2 v[32:33], v11, s[16:17]
	s_add_u32 s14, s14, 0x20000
	s_addc_u32 s15, s15, 0
	s_add_u32 s16, s16, 0x20000
	s_addc_u32 s17, s17, 0
	global_load_dwordx4 v[34:37], v10, s[14:15] offset:0
	global_load_dwordx4 v[38:41], v10, s[14:15] offset:64
	global_load_dwordx4 v[42:45], v10, s[14:15] offset:128
	global_load_dwordx4 v[46:49], v10, s[14:15] offset:192
	global_load_dwordx2 v[50:51], v11, s[16:17]
	s_add_u32 s14, s14, 0x20000
	s_addc_u32 s15, s15, 0
	s_add_u32 s16, s16, 0x20000
	s_addc_u32 s17, s17, 0
	global_load_dwordx4 v[52:55], v10, s[14:15] offset:0
	global_load_dwordx4 v[56:59], v10, s[14:15] offset:64
	global_load_dwordx4 v[60:63], v10, s[14:15] offset:128
	global_load_dwordx4 v[64:67], v10, s[14:15] offset:192
	global_load_dwordx2 v[68:69], v11, s[16:17]
	s_add_u32 s14, s14, 0x20000
	s_addc_u32 s15, s15, 0
	s_add_u32 s16, s16, 0x20000
	s_addc_u32 s17, s17, 0
	global_load_dwordx4 v[70:73], v10, s[14:15] offset:0
	global_load_dwordx4 v[74:77], v10, s[14:15] offset:64
	global_load_dwordx4 v[78:81], v10, s[14:15] offset:128
	global_load_dwordx4 v[82:85], v10, s[14:15] offset:192
	global_load_dwordx2 v[86:87], v11, s[16:17]
	s_add_u32 s14, s14, 0x20000
	s_addc_u32 s15, s15, 0
	s_add_u32 s16, s16, 0x20000
	s_addc_u32 s17, s17, 0
	global_load_dwordx4 v[88:91], v10, s[14:15] offset:0
	global_load_dwordx4 v[92:95], v10, s[14:15] offset:64
	global_load_dwordx4 v[96:99], v10, s[14:15] offset:128
	global_load_dwordx4 v[100:103], v10, s[14:15] offset:192
	global_load_dwordx2 v[104:105], v11, s[16:17]
	s_add_u32 s14, s14, 0x20000
	s_addc_u32 s15, s15, 0
	s_add_u32 s16, s16, 0x20000
	s_addc_u32 s17, s17, 0
	global_load_dwordx4 v[106:109], v10, s[14:15] offset:0
	global_load_dwordx4 v[110:113], v10, s[14:15] offset:64
	global_load_dwordx4 v[114:117], v10, s[14:15] offset:128
	global_load_dwordx4 v[118:121], v10, s[14:15] offset:192
	global_load_dwordx2 v[122:123], v11, s[16:17]
	s_add_u32 s14, s14, 0x20000
	s_addc_u32 s15, s15, 0
	s_add_u32 s16, s16, 0x20000
	s_addc_u32 s17, s17, 0
	ds_read_b128 v[144:147], v12 offset:0
	ds_read_b128 v[148:151], v12 offset:64
	ds_read_b128 v[152:155], v12 offset:128
	ds_read_b128 v[156:159], v12 offset:192
	ds_read_b128 v[136:139], v7
	s_waitcnt vmcnt(25)
	s_waitcnt lgkmcnt(4)
	v_mfma_f32_16x16x32_bf16 v[124:127], v[16:19], v[144:147], 0
	s_waitcnt lgkmcnt(3)
	v_mfma_f32_16x16x32_bf16 v[124:127], v[20:23], v[148:151], v[124:127]
	s_waitcnt lgkmcnt(2)
	v_mfma_f32_16x16x32_bf16 v[124:127], v[24:27], v[152:155], v[124:127]
	s_waitcnt lgkmcnt(1)
	v_mfma_f32_16x16x32_bf16 v[124:127], v[28:31], v[156:159], v[124:127]
	v_lshlrev_b32_e32 v128, 16, v32
	v_and_b32_e32 v129, 0xffff0000, v32
	v_lshlrev_b32_e32 v130, 16, v33
	v_and_b32_e32 v131, 0xffff0000, v33
	s_nop 4
	v_sub_f32_e32 v128, v128, v124
	v_sub_f32_e32 v129, v129, v125
	v_sub_f32_e32 v130, v130, v126
	v_sub_f32_e32 v131, v131, v127
	v_cvt_pk_bf16_f32 v132, v128, v129
	v_cvt_pk_bf16_f32 v133, v130, v131
	ds_write_b64 v13, v[132:133]
	s_waitcnt lgkmcnt(0)
	s_barrier
	global_store_dwordx4 v6, v[136:139], s[6:7]
	s_add_u32 s6, s6, 0x40000
	s_addc_u32 s7, s7, 0
	ds_read_b64 v[140:141], v8
	global_load_dwordx4 v[16:19], v10, s[14:15] offset:0
	global_load_dwordx4 v[20:23], v10, s[14:15] offset:64
	global_load_dwordx4 v[24:27], v10, s[14:15] offset:128
	global_load_dwordx4 v[28:31], v10, s[14:15] offset:192
	global_load_dwordx2 v[32:33], v11, s[16:17]
	s_add_u32 s14, s14, 0x20000
	s_addc_u32 s15, s15, 0
	s_add_u32 s16, s16, 0x20000
	s_addc_u32 s17, s17, 0
	s_waitcnt lgkmcnt(0)
	global_store_dwordx2 v9, v[140:141], s[18:19]
	s_add_u32 s18, s18, 0x20000
	s_addc_u32 s19, s19, 0
	s_barrier
; __device__ __forceinline__ u32x2 pk4(f32x4 v) { u32x2 r; r.x = pk2(v[0], v[1]); r.y = pk2(v[2], v[3]); return r; }
; __device__ __forceinline__ f32x4 up4(u32x2 u) { return (f32x4){lo16(u.x), hi16(u.x), lo16(u.y), hi16(u.y)}; }
; __device__ __forceinline__ f32x4 mfma16(bf16x8 a, bf16x8 b, f32x4 c) { return __builtin_amdgcn_mfma_f32_16x16x32_bf16(a, b, c, 0, 0, 0); }
; __device__ __forceinline__ void dn_stage_load(DnStage& S, const bf16_t* dW, const bf16_t* dUT, const bf16_t* dKdT, const float* dGl, int ck, int h, int vs, int wave, int r, int q) {
;     const int cc = ck < NCH ? ck : NCH - 1; const size_t ch = (size_t)(cc * 8 + h);
;     if (wave < 4) {
; #pragma unroll
;         for (int kk = 0; kk < 4; ++kk) S.f[kk] = ldfrag(dW + (ch * 64 + wave * 16 + r) * 128 + kk * 32 + q * 8);
;         S.u = *(const u32x2*)(dUT + (ch * 128 + vs * 16 + r) * 64 + wave * 16 + 4 * q);
; __device__ __forceinline__ void dn_step(const DnStage& S, f32x4 (&Sacc)[2], bf16_t* ST, bf16_t* VN, bf16_t* dVnT, bf16_t* dST, int ck, int h, int vs, int wave, int r, int q) {
;     const size_t ch = (size_t)(ck * 8 + h);
;     if (wave < 4) {
;         bf16x8 sf[4];
; #pragma unroll
;         for (int kk = 0; kk < 4; ++kk) sf[kk] = *(const bf16x8*)(ST + r * 136 + kk * 32 + q * 8);
;         f32x4 a = (f32x4){0.f, 0.f, 0.f, 0.f};
; #pragma unroll
;         for (int kk = 0; kk < 4; ++kk) a = mfma16(S.f[kk], sf[kk], a);
;         const f32x4 vn = up4(S.u) - a; const u32x2 pv = pk4(vn);
;         *(u32x2*)(VN + r * 72 + wave * 16 + 4 * q) = pv;
;         *(u32x2*)(dVnT + (ch * 128 + vs * 16 + r) * 64 + wave * 16 + 4 * q) = pv;
;     }
;     asm volatile("s_waitcnt lgkmcnt(0)" ::: "memory"); __builtin_amdgcn_s_barrier(); asm volatile("" ::: "memory");
	ds_read_b128 v[144:147], v12 offset:0
	ds_read_b128 v[148:151], v12 offset:64
	ds_read_b128 v[152:155], v12 offset:128
	ds_read_b128 v[156:159], v12 offset:192
	ds_read_b128 v[136:139], v7
	s_waitcnt vmcnt(27)
	s_waitcnt lgkmcnt(4)
	v_mfma_f32_16x16x32_bf16 v[124:127], v[34:37], v[144:147], 0
	s_waitcnt lgkmcnt(3)
	v_mfma_f32_16x16x32_bf16 v[124:127], v[38:41], v[148:151], v[124:127]
	s_waitcnt lgkmcnt(2)
	v_mfma_f32_16x16x32_bf16 v[124:127], v[42:45], v[152:155], v[124:127]
	s_waitcnt lgkmcnt(1)
	v_mfma_f32_16x16x32_bf16 v[124:127], v[46:49], v[156:159], v[124:127]
	v_lshlrev_b32_e32 v128, 16, v50
	v_and_b32_e32 v129, 0xffff0000, v50
	v_lshlrev_b32_e32 v130, 16, v51
	v_and_b32_e32 v131, 0xffff0000, v51
	s_nop 4
	v_sub_f32_e32 v128, v128, v124
	v_sub_f32_e32 v129, v129, v125
	v_sub_f32_e32 v130, v130, v126
	v_sub_f32_e32 v131, v131, v127
	v_cvt_pk_bf16_f32 v132, v128, v129
	v_cvt_pk_bf16_f32 v133, v130, v131
	ds_write_b64 v13, v[132:133]
	s_waitcnt lgkmcnt(0)
	s_barrier
	global_store_dwordx4 v6, v[136:139], s[6:7]
	s_add_u32 s6, s6, 0x40000
	s_addc_u32 s7, s7, 0
	ds_read_b64 v[140:141], v8
	global_load_dwordx4 v[34:37], v10, s[14:15] offset:0
	global_load_dwordx4 v[38:41], v10, s[14:15] offset:64
	global_load_dwordx4 v[42:45], v10, s[14:15] offset:128
	global_load_dwordx4 v[46:49], v10, s[14:15] offset:192
	global_load_dwordx2 v[50:51], v11, s[16:17]
	s_add_u32 s14, s14, 0x20000
	s_addc_u32 s15, s15, 0
	s_add_u32 s16, s16, 0x20000
	s_addc_u32 s17, s17, 0
	s_waitcnt lgkmcnt(0)
	global_store_dwordx2 v9, v[140:141], s[18:19]
	s_add_u32 s18, s18, 0x20000
	s_addc_u32 s19, s19, 0
	s_barrier
	ds_read_b128 v[144:147], v12 offset:0
	ds_read_b128 v[148:151], v12 offset:64
	ds_read_b128 v[152:155], v12 offset:128
	ds_read_b128 v[156:159], v12 offset:192
	ds_read_b128 v[136:139], v7
	s_waitcnt vmcnt(29)
	s_waitcnt lgkmcnt(4)
	v_mfma_f32_16x16x32_bf16 v[124:127], v[52:55], v[144:147], 0
	s_waitcnt lgkmcnt(3)
	v_mfma_f32_16x16x32_bf16 v[124:127], v[56:59], v[148:151], v[124:127]
	s_waitcnt lgkmcnt(2)
	v_mfma_f32_16x16x32_bf16 v[124:127], v[60:63], v[152:155], v[124:127]
	s_waitcnt lgkmcnt(1)
	v_mfma_f32_16x16x32_bf16 v[124:127], v[64:67], v[156:159], v[124:127]
	v_lshlrev_b32_e32 v128, 16, v68
	v_and_b32_e32 v129, 0xffff0000, v68
	v_lshlrev_b32_e32 v130, 16, v69
	v_and_b32_e32 v131, 0xffff0000, v69
	s_nop 4
	v_sub_f32_e32 v128, v128, v124
	v_sub_f32_e32 v129, v129, v125
	v_sub_f32_e32 v130, v130, v126
	v_sub_f32_e32 v131, v131, v127
	v_cvt_pk_bf16_f32 v132, v128, v129
	v_cvt_pk_bf16_f32 v133, v130, v131
	ds_write_b64 v13, v[132:133]
	s_waitcnt lgkmcnt(0)
	s_barrier
	global_store_dwordx4 v6, v[136:139], s[6:7]
	s_add_u32 s6, s6, 0x40000
	s_addc_u32 s7, s7, 0
	ds_read_b64 v[140:141], v8
	global_load_dwordx4 v[52:55], v10, s[14:15] offset:0
	global_load_dwordx4 v[56:59], v10, s[14:15] offset:64
	global_load_dwordx4 v[60:63], v10, s[14:15] offset:128
	global_load_dwordx4 v[64:67], v10, s[14:15] offset:192
	global_load_dwordx2 v[68:69], v11, s[16:17]
	s_add_u32 s14, s14, 0x20000
	s_addc_u32 s15, s15, 0
	s_add_u32 s16, s16, 0x20000
	s_addc_u32 s17, s17, 0
	s_waitcnt lgkmcnt(0)
	global_store_dwordx2 v9, v[140:141], s[18:19]
	s_add_u32 s18, s18, 0x20000
	s_addc_u32 s19, s19, 0
	s_barrier
	ds_read_b128 v[144:147], v12 offset:0
	ds_read_b128 v[148:151], v12 offset:64
	ds_read_b128 v[152:155], v12 offset:128
	ds_read_b128 v[156:159], v12 offset:192
	ds_read_b128 v[136:139], v7
	s_waitcnt vmcnt(31)
	s_waitcnt lgkmcnt(4)
	v_mfma_f32_16x16x32_bf16 v[124:127], v[70:73], v[144:147], 0
	s_waitcnt lgkmcnt(3)
	v_mfma_f32_16x16x32_bf16 v[124:127], v[74:77], v[148:151], v[124:127]
	s_waitcnt lgkmcnt(2)
	v_mfma_f32_16x16x32_bf16 v[124:127], v[78:81], v[152:155], v[124:127]
	s_waitcnt lgkmcnt(1)
	v_mfma_f32_16x16x32_bf16 v[124:127], v[82:85], v[156:159], v[124:127]
	v_lshlrev_b32_e32 v128, 16, v86
	v_and_b32_e32 v129, 0xffff0000, v86
	v_lshlrev_b32_e32 v130, 16, v87
	v_and_b32_e32 v131, 0xffff0000, v87
	s_nop 4
	v_sub_f32_e32 v128, v128, v124
	v_sub_f32_e32 v129, v129, v125
	v_sub_f32_e32 v130, v130, v126
	v_sub_f32_e32 v131, v131, v127
	v_cvt_pk_bf16_f32 v132, v128, v129
	v_cvt_pk_bf16_f32 v133, v130, v131
	ds_write_b64 v13, v[132:133]
	s_waitcnt lgkmcnt(0)
	s_barrier
	global_store_dwordx4 v6, v[136:139], s[6:7]
	s_add_u32 s6, s6, 0x40000
	s_addc_u32 s7, s7, 0
	ds_read_b64 v[140:141], v8
	global_load_dwordx4 v[70:73], v10, s[14:15] offset:0
	global_load_dwordx4 v[74:77], v10, s[14:15] offset:64
	global_load_dwordx4 v[78:81], v10, s[14:15] offset:128
	global_load_dwordx4 v[82:85], v10, s[14:15] offset:192
	global_load_dwordx2 v[86:87], v11, s[16:17]
	s_add_u32 s14, s14, 0x20000
	s_addc_u32 s15, s15, 0
	s_add_u32 s16, s16, 0x20000
	s_addc_u32 s17, s17, 0
	s_waitcnt lgkmcnt(0)
	global_store_dwordx2 v9, v[140:141], s[18:19]
	s_add_u32 s18, s18, 0x20000
	s_addc_u32 s19, s19, 0
	s_barrier
	ds_read_b128 v[144:147], v12 offset:0
	ds_read_b128 v[148:151], v12 offset:64
	ds_read_b128 v[152:155], v12 offset:128
	ds_read_b128 v[156:159], v12 offset:192
	ds_read_b128 v[136:139], v7
	s_waitcnt vmcnt(33)
	s_waitcnt lgkmcnt(4)
	v_mfma_f32_16x16x32_bf16 v[124:127], v[88:91], v[144:147], 0
	s_waitcnt lgkmcnt(3)
	v_mfma_f32_16x16x32_bf16 v[124:127], v[92:95], v[148:151], v[124:127]
	s_waitcnt lgkmcnt(2)
	v_mfma_f32_16x16x32_bf16 v[124:127], v[96:99], v[152:155], v[124:127]
	s_waitcnt lgkmcnt(1)
	v_mfma_f32_16x16x32_bf16 v[124:127], v[100:103], v[156:159], v[124:127]
	v_lshlrev_b32_e32 v128, 16, v104
	v_and_b32_e32 v129, 0xffff0000, v104
	v_lshlrev_b32_e32 v130, 16, v105
	v_and_b32_e32 v131, 0xffff0000, v105
	s_nop 4
	v_sub_f32_e32 v128, v128, v124
	v_sub_f32_e32 v129, v129, v125
	v_sub_f32_e32 v130, v130, v126
	v_sub_f32_e32 v131, v131, v127
	v_cvt_pk_bf16_f32 v132, v128, v129
	v_cvt_pk_bf16_f32 v133, v130, v131
	ds_write_b64 v13, v[132:133]
	s_waitcnt lgkmcnt(0)
	s_barrier
; __device__ __forceinline__ u32x2 pk4(f32x4 v) { u32x2 r; r.x = pk2(v[0], v[1]); r.y = pk2(v[2], v[3]); return r; }
; __device__ __forceinline__ f32x4 up4(u32x2 u) { return (f32x4){lo16(u.x), hi16(u.x), lo16(u.y), hi16(u.y)}; }
; __device__ __forceinline__ f32x4 mfma16(bf16x8 a, bf16x8 b, f32x4 c) { return __builtin_amdgcn_mfma_f32_16x16x32_bf16(a, b, c, 0, 0, 0); }
; __device__ __forceinline__ void dn_stage_load(DnStage& S, const bf16_t* dW, const bf16_t* dUT, const bf16_t* dKdT, const float* dGl, int ck, int h, int vs, int wave, int r, int q) {
;     const int cc = ck < NCH ? ck : NCH - 1; const size_t ch = (size_t)(cc * 8 + h);
;     if (wave < 4) {
; #pragma unroll
;         for (int kk = 0; kk < 4; ++kk) S.f[kk] = ldfrag(dW + (ch * 64 + wave * 16 + r) * 128 + kk * 32 + q * 8);
;         S.u = *(const u32x2*)(dUT + (ch * 128 + vs * 16 + r) * 64 + wave * 16 + 4 * q);
; __device__ __forceinline__ void dn_step(const DnStage& S, f32x4 (&Sacc)[2], bf16_t* ST, bf16_t* VN, bf16_t* dVnT, bf16_t* dST, int ck, int h, int vs, int wave, int r, int q) {
;     const size_t ch = (size_t)(ck * 8 + h);
;     if (wave < 4) {
;         bf16x8 sf[4];
; #pragma unroll
;         for (int kk = 0; kk < 4; ++kk) sf[kk] = *(const bf16x8*)(ST + r * 136 + kk * 32 + q * 8);
;         f32x4 a = (f32x4){0.f, 0.f, 0.f, 0.f};
; #pragma unroll
;         for (int kk = 0; kk < 4; ++kk) a = mfma16(S.f[kk], sf[kk], a);
;         const f32x4 vn = up4(S.u) - a; const u32x2 pv = pk4(vn);
;         *(u32x2*)(VN + r * 72 + wave * 16 + 4 * q) = pv;
;         *(u32x2*)(dVnT + (ch * 128 + vs * 16 + r) * 64 + wave * 16 + 4 * q) = pv;
;     }
;     asm volatile("s_waitcnt lgkmcnt(0)" ::: "memory"); __builtin_amdgcn_s_barrier(); asm volatile("" ::: "memory");
	global_store_dwordx4 v6, v[136:139], s[6:7]
	s_add_u32 s6, s6, 0x40000
	s_addc_u32 s7, s7, 0
	ds_read_b64 v[140:141], v8
	global_load_dwordx4 v[88:91], v10, s[14:15] offset:0
	global_load_dwordx4 v[92:95], v10, s[14:15] offset:64
	global_load_dwordx4 v[96:99], v10, s[14:15] offset:128
	global_load_dwordx4 v[100:103], v10, s[14:15] offset:192
	global_load_dwordx2 v[104:105], v11, s[16:17]
	s_add_u32 s14, s14, 0x20000
	s_addc_u32 s15, s15, 0
	s_add_u32 s16, s16, 0x20000
	s_addc_u32 s17, s17, 0
	s_waitcnt lgkmcnt(0)
	global_store_dwordx2 v9, v[140:141], s[18:19]
	s_add_u32 s18, s18, 0x20000
	s_addc_u32 s19, s19, 0
	s_barrier
	ds_read_b128 v[144:147], v12 offset:0
	ds_read_b128 v[148:151], v12 offset:64
	ds_read_b128 v[152:155], v12 offset:128
	ds_read_b128 v[156:159], v12 offset:192
	ds_read_b128 v[136:139], v7
	s_waitcnt vmcnt(35)
	s_waitcnt lgkmcnt(4)
	v_mfma_f32_16x16x32_bf16 v[124:127], v[106:109], v[144:147], 0
	s_waitcnt lgkmcnt(3)
	v_mfma_f32_16x16x32_bf16 v[124:127], v[110:113], v[148:151], v[124:127]
	s_waitcnt lgkmcnt(2)
	v_mfma_f32_16x16x32_bf16 v[124:127], v[114:117], v[152:155], v[124:127]
	s_waitcnt lgkmcnt(1)
	v_mfma_f32_16x16x32_bf16 v[124:127], v[118:121], v[156:159], v[124:127]
	v_lshlrev_b32_e32 v128, 16, v122
	v_and_b32_e32 v129, 0xffff0000, v122
	v_lshlrev_b32_e32 v130, 16, v123
	v_and_b32_e32 v131, 0xffff0000, v123
	s_nop 4
	v_sub_f32_e32 v128, v128, v124
	v_sub_f32_e32 v129, v129, v125
	v_sub_f32_e32 v130, v130, v126
	v_sub_f32_e32 v131, v131, v127
	v_cvt_pk_bf16_f32 v132, v128, v129
	v_cvt_pk_bf16_f32 v133, v130, v131
	ds_write_b64 v13, v[132:133]
	s_waitcnt lgkmcnt(0)
	s_barrier
	global_store_dwordx4 v6, v[136:139], s[6:7]
	s_add_u32 s6, s6, 0x40000
	s_addc_u32 s7, s7, 0
	ds_read_b64 v[140:141], v8
	global_load_dwordx4 v[106:109], v10, s[14:15] offset:0
	global_load_dwordx4 v[110:113], v10, s[14:15] offset:64
	global_load_dwordx4 v[114:117], v10, s[14:15] offset:128
	global_load_dwordx4 v[118:121], v10, s[14:15] offset:192
	global_load_dwordx2 v[122:123], v11, s[16:17]
	s_add_u32 s14, s14, 0x20000
	s_addc_u32 s15, s15, 0
	s_add_u32 s16, s16, 0x20000
	s_addc_u32 s17, s17, 0
	s_waitcnt lgkmcnt(0)
	global_store_dwordx2 v9, v[140:141], s[18:19]
	s_add_u32 s18, s18, 0x20000
	s_addc_u32 s19, s19, 0
	s_barrier
	ds_read_b128 v[144:147], v12 offset:0
	ds_read_b128 v[148:151], v12 offset:64
	ds_read_b128 v[152:155], v12 offset:128
	ds_read_b128 v[156:159], v12 offset:192
	ds_read_b128 v[136:139], v7
	s_waitcnt vmcnt(36)
	s_waitcnt lgkmcnt(4)
	v_mfma_f32_16x16x32_bf16 v[124:127], v[16:19], v[144:147], 0
	s_waitcnt lgkmcnt(3)
	v_mfma_f32_16x16x32_bf16 v[124:127], v[20:23], v[148:151], v[124:127]
	s_waitcnt lgkmcnt(2)
	v_mfma_f32_16x16x32_bf16 v[124:127], v[24:27], v[152:155], v[124:127]
	s_waitcnt lgkmcnt(1)
	v_mfma_f32_16x16x32_bf16 v[124:127], v[28:31], v[156:159], v[124:127]
	v_lshlrev_b32_e32 v128, 16, v32
	v_and_b32_e32 v129, 0xffff0000, v32
	v_lshlrev_b32_e32 v130, 16, v33
	v_and_b32_e32 v131, 0xffff0000, v33
	s_nop 4
	v_sub_f32_e32 v128, v128, v124
	v_sub_f32_e32 v129, v129, v125
	v_sub_f32_e32 v130, v130, v126
	v_sub_f32_e32 v131, v131, v127
	v_cvt_pk_bf16_f32 v132, v128, v129
	v_cvt_pk_bf16_f32 v133, v130, v131
	ds_write_b64 v13, v[132:133]
	s_waitcnt lgkmcnt(0)
	s_barrier
	global_store_dwordx4 v6, v[136:139], s[6:7]
	s_add_u32 s6, s6, 0x40000
	s_addc_u32 s7, s7, 0
	ds_read_b64 v[140:141], v8
	global_load_dwordx4 v[16:19], v10, s[14:15] offset:0
	global_load_dwordx4 v[20:23], v10, s[14:15] offset:64
	global_load_dwordx4 v[24:27], v10, s[14:15] offset:128
	global_load_dwordx4 v[28:31], v10, s[14:15] offset:192
	global_load_dwordx2 v[32:33], v11, s[16:17]
	s_add_u32 s14, s14, 0x20000
	s_addc_u32 s15, s15, 0
	s_add_u32 s16, s16, 0x20000
	s_addc_u32 s17, s17, 0
	s_waitcnt lgkmcnt(0)
	global_store_dwordx2 v9, v[140:141], s[18:19]
	s_add_u32 s18, s18, 0x20000
	s_addc_u32 s19, s19, 0
	s_barrier
	ds_read_b128 v[144:147], v12 offset:0
	ds_read_b128 v[148:151], v12 offset:64
	ds_read_b128 v[152:155], v12 offset:128
	ds_read_b128 v[156:159], v12 offset:192
	ds_read_b128 v[136:139], v7
	s_waitcnt vmcnt(36)
	s_waitcnt lgkmcnt(4)
	v_mfma_f32_16x16x32_bf16 v[124:127], v[34:37], v[144:147], 0
	s_waitcnt lgkmcnt(3)
	v_mfma_f32_16x16x32_bf16 v[124:127], v[38:41], v[148:151], v[124:127]
	s_waitcnt lgkmcnt(2)
	v_mfma_f32_16x16x32_bf16 v[124:127], v[42:45], v[152:155], v[124:127]
	s_waitcnt lgkmcnt(1)
	v_mfma_f32_16x16x32_bf16 v[124:127], v[46:49], v[156:159], v[124:127]
	v_lshlrev_b32_e32 v128, 16, v50
	v_and_b32_e32 v129, 0xffff0000, v50
	v_lshlrev_b32_e32 v130, 16, v51
	v_and_b32_e32 v131, 0xffff0000, v51
	s_nop 4
	v_sub_f32_e32 v128, v128, v124
	v_sub_f32_e32 v129, v129, v125
	v_sub_f32_e32 v130, v130, v126
	v_sub_f32_e32 v131, v131, v127
	v_cvt_pk_bf16_f32 v132, v128, v129
	v_cvt_pk_bf16_f32 v133, v130, v131
	ds_write_b64 v13, v[132:133]
	s_waitcnt lgkmcnt(0)
	s_barrier
	global_store_dwordx4 v6, v[136:139], s[6:7]
	s_add_u32 s6, s6, 0x40000
	s_addc_u32 s7, s7, 0
	ds_read_b64 v[140:141], v8
	global_load_dwordx4 v[34:37], v10, s[14:15] offset:0
	global_load_dwordx4 v[38:41], v10, s[14:15] offset:64
	global_load_dwordx4 v[42:45], v10, s[14:15] offset:128
	global_load_dwordx4 v[46:49], v10, s[14:15] offset:192
	global_load_dwordx2 v[50:51], v11, s[16:17]
	s_add_u32 s14, s14, 0x20000
	s_addc_u32 s15, s15, 0
	s_add_u32 s16, s16, 0x20000
	s_addc_u32 s17, s17, 0
	s_waitcnt lgkmcnt(0)
	global_store_dwordx2 v9, v[140:141], s[18:19]
	s_add_u32 s18, s18, 0x20000
	s_addc_u32 s19, s19, 0
	s_barrier
	s_mov_b32 s20, 19
; __device__ __forceinline__ u32x2 pk4(f32x4 v) { u32x2 r; r.x = pk2(v[0], v[1]); r.y = pk2(v[2], v[3]); return r; }
; __device__ __forceinline__ f32x4 up4(u32x2 u) { return (f32x4){lo16(u.x), hi16(u.x), lo16(u.y), hi16(u.y)}; }
; __device__ __forceinline__ f32x4 mfma16(bf16x8 a, bf16x8 b, f32x4 c) { return __builtin_amdgcn_mfma_f32_16x16x32_bf16(a, b, c, 0, 0, 0); }
; __device__ __forceinline__ void dn_stage_load(DnStage& S, const bf16_t* dW, const bf16_t* dUT, const bf16_t* dKdT, const float* dGl, int ck, int h, int vs, int wave, int r, int q) {
;     const int cc = ck < NCH ? ck : NCH - 1; const size_t ch = (size_t)(cc * 8 + h);
;     if (wave < 4) {
; #pragma unroll
;         for (int kk = 0; kk < 4; ++kk) S.f[kk] = ldfrag(dW + (ch * 64 + wave * 16 + r) * 128 + kk * 32 + q * 8);
;         S.u = *(const u32x2*)(dUT + (ch * 128 + vs * 16 + r) * 64 + wave * 16 + 4 * q);
; __device__ __forceinline__ void dn_step(const DnStage& S, f32x4 (&Sacc)[2], bf16_t* ST, bf16_t* VN, bf16_t* dVnT, bf16_t* dST, int ck, int h, int vs, int wave, int r, int q) {
;     const size_t ch = (size_t)(ck * 8 + h);
;     if (wave < 4) {
;         bf16x8 sf[4];
; #pragma unroll
;         for (int kk = 0; kk < 4; ++kk) sf[kk] = *(const bf16x8*)(ST + r * 136 + kk * 32 + q * 8);
;         f32x4 a = (f32x4){0.f, 0.f, 0.f, 0.f};
; #pragma unroll
;         for (int kk = 0; kk < 4; ++kk) a = mfma16(S.f[kk], sf[kk], a);
;         const f32x4 vn = up4(S.u) - a; const u32x2 pv = pk4(vn);
;         *(u32x2*)(VN + r * 72 + wave * 16 + 4 * q) = pv;
;         *(u32x2*)(dVnT + (ch * 128 + vs * 16 + r) * 64 + wave * 16 + 4 * q) = pv;
;     }
;     asm volatile("s_waitcnt lgkmcnt(0)" ::: "memory"); __builtin_amdgcn_s_barrier(); asm volatile("" ::: "memory");
.Ldq_A_loop:
	ds_read_b128 v[144:147], v12 offset:0
	ds_read_b128 v[148:151], v12 offset:64
	ds_read_b128 v[152:155], v12 offset:128
	ds_read_b128 v[156:159], v12 offset:192
	ds_read_b128 v[136:139], v7
	s_waitcnt vmcnt(36)
	s_waitcnt lgkmcnt(4)
	v_mfma_f32_16x16x32_bf16 v[124:127], v[52:55], v[144:147], 0
	s_waitcnt lgkmcnt(3)
	v_mfma_f32_16x16x32_bf16 v[124:127], v[56:59], v[148:151], v[124:127]
	s_waitcnt lgkmcnt(2)
	v_mfma_f32_16x16x32_bf16 v[124:127], v[60:63], v[152:155], v[124:127]
	s_waitcnt lgkmcnt(1)
	v_mfma_f32_16x16x32_bf16 v[124:127], v[64:67], v[156:159], v[124:127]
	v_lshlrev_b32_e32 v128, 16, v68
	v_and_b32_e32 v129, 0xffff0000, v68
	v_lshlrev_b32_e32 v130, 16, v69
	v_and_b32_e32 v131, 0xffff0000, v69
	s_nop 4
	v_sub_f32_e32 v128, v128, v124
	v_sub_f32_e32 v129, v129, v125
	v_sub_f32_e32 v130, v130, v126
	v_sub_f32_e32 v131, v131, v127
	v_cvt_pk_bf16_f32 v132, v128, v129
	v_cvt_pk_bf16_f32 v133, v130, v131
	ds_write_b64 v13, v[132:133]
	s_waitcnt lgkmcnt(0)
	s_barrier
	global_store_dwordx4 v6, v[136:139], s[6:7]
	s_add_u32 s6, s6, 0x40000
	s_addc_u32 s7, s7, 0
	ds_read_b64 v[140:141], v8
	global_load_dwordx4 v[52:55], v10, s[14:15] offset:0
	global_load_dwordx4 v[56:59], v10, s[14:15] offset:64
	global_load_dwordx4 v[60:63], v10, s[14:15] offset:128
	global_load_dwordx4 v[64:67], v10, s[14:15] offset:192
	global_load_dwordx2 v[68:69], v11, s[16:17]
	s_add_u32 s14, s14, 0x20000
	s_addc_u32 s15, s15, 0
	s_add_u32 s16, s16, 0x20000
	s_addc_u32 s17, s17, 0
	s_waitcnt lgkmcnt(0)
	global_store_dwordx2 v9, v[140:141], s[18:19]
	s_add_u32 s18, s18, 0x20000
	s_addc_u32 s19, s19, 0
	s_barrier
	ds_read_b128 v[144:147], v12 offset:0
	ds_read_b128 v[148:151], v12 offset:64
	ds_read_b128 v[152:155], v12 offset:128
	ds_read_b128 v[156:159], v12 offset:192
	ds_read_b128 v[136:139], v7
	s_waitcnt vmcnt(36)
	s_waitcnt lgkmcnt(4)
	v_mfma_f32_16x16x32_bf16 v[124:127], v[70:73], v[144:147], 0
	s_waitcnt lgkmcnt(3)
	v_mfma_f32_16x16x32_bf16 v[124:127], v[74:77], v[148:151], v[124:127]
	s_waitcnt lgkmcnt(2)
	v_mfma_f32_16x16x32_bf16 v[124:127], v[78:81], v[152:155], v[124:127]
	s_waitcnt lgkmcnt(1)
	v_mfma_f32_16x16x32_bf16 v[124:127], v[82:85], v[156:159], v[124:127]
	v_lshlrev_b32_e32 v128, 16, v86
	v_and_b32_e32 v129, 0xffff0000, v86
	v_lshlrev_b32_e32 v130, 16, v87
	v_and_b32_e32 v131, 0xffff0000, v87
	s_nop 4
	v_sub_f32_e32 v128, v128, v124
	v_sub_f32_e32 v129, v129, v125
	v_sub_f32_e32 v130, v130, v126
	v_sub_f32_e32 v131, v131, v127
	v_cvt_pk_bf16_f32 v132, v128, v129
	v_cvt_pk_bf16_f32 v133, v130, v131
	ds_write_b64 v13, v[132:133]
	s_waitcnt lgkmcnt(0)
	s_barrier
	global_store_dwordx4 v6, v[136:139], s[6:7]
	s_add_u32 s6, s6, 0x40000
	s_addc_u32 s7, s7, 0
	ds_read_b64 v[140:141], v8
	global_load_dwordx4 v[70:73], v10, s[14:15] offset:0
	global_load_dwordx4 v[74:77], v10, s[14:15] offset:64
	global_load_dwordx4 v[78:81], v10, s[14:15] offset:128
	global_load_dwordx4 v[82:85], v10, s[14:15] offset:192
	global_load_dwordx2 v[86:87], v11, s[16:17]
	s_add_u32 s14, s14, 0x20000
	s_addc_u32 s15, s15, 0
	s_add_u32 s16, s16, 0x20000
	s_addc_u32 s17, s17, 0
	s_waitcnt lgkmcnt(0)
	global_store_dwordx2 v9, v[140:141], s[18:19]
	s_add_u32 s18, s18, 0x20000
	s_addc_u32 s19, s19, 0
	s_barrier
	ds_read_b128 v[144:147], v12 offset:0
	ds_read_b128 v[148:151], v12 offset:64
	ds_read_b128 v[152:155], v12 offset:128
	ds_read_b128 v[156:159], v12 offset:192
	ds_read_b128 v[136:139], v7
	s_waitcnt vmcnt(36)
	s_waitcnt lgkmcnt(4)
	v_mfma_f32_16x16x32_bf16 v[124:127], v[88:91], v[144:147], 0
	s_waitcnt lgkmcnt(3)
	v_mfma_f32_16x16x32_bf16 v[124:127], v[92:95], v[148:151], v[124:127]
	s_waitcnt lgkmcnt(2)
	v_mfma_f32_16x16x32_bf16 v[124:127], v[96:99], v[152:155], v[124:127]
	s_waitcnt lgkmcnt(1)
	v_mfma_f32_16x16x32_bf16 v[124:127], v[100:103], v[156:159], v[124:127]
	v_lshlrev_b32_e32 v128, 16, v104
	v_and_b32_e32 v129, 0xffff0000, v104
	v_lshlrev_b32_e32 v130, 16, v105
	v_and_b32_e32 v131, 0xffff0000, v105
	s_nop 4
	v_sub_f32_e32 v128, v128, v124
	v_sub_f32_e32 v129, v129, v125
	v_sub_f32_e32 v130, v130, v126
	v_sub_f32_e32 v131, v131, v127
	v_cvt_pk_bf16_f32 v132, v128, v129
	v_cvt_pk_bf16_f32 v133, v130, v131
	ds_write_b64 v13, v[132:133]
	s_waitcnt lgkmcnt(0)
	s_barrier
	global_store_dwordx4 v6, v[136:139], s[6:7]
	s_add_u32 s6, s6, 0x40000
	s_addc_u32 s7, s7, 0
	ds_read_b64 v[140:141], v8
	global_load_dwordx4 v[88:91], v10, s[14:15] offset:0
	global_load_dwordx4 v[92:95], v10, s[14:15] offset:64
	global_load_dwordx4 v[96:99], v10, s[14:15] offset:128
	global_load_dwordx4 v[100:103], v10, s[14:15] offset:192
	global_load_dwordx2 v[104:105], v11, s[16:17]
	s_add_u32 s14, s14, 0x20000
	s_addc_u32 s15, s15, 0
	s_add_u32 s16, s16, 0x20000
	s_addc_u32 s17, s17, 0
	s_waitcnt lgkmcnt(0)
	global_store_dwordx2 v9, v[140:141], s[18:19]
	s_add_u32 s18, s18, 0x20000
	s_addc_u32 s19, s19, 0
	s_barrier
	ds_read_b128 v[144:147], v12 offset:0
	ds_read_b128 v[148:151], v12 offset:64
	ds_read_b128 v[152:155], v12 offset:128
	ds_read_b128 v[156:159], v12 offset:192
	ds_read_b128 v[136:139], v7
	s_waitcnt vmcnt(36)
	s_waitcnt lgkmcnt(4)
	v_mfma_f32_16x16x32_bf16 v[124:127], v[106:109], v[144:147], 0
	s_waitcnt lgkmcnt(3)
	v_mfma_f32_16x16x32_bf16 v[124:127], v[110:113], v[148:151], v[124:127]
	s_waitcnt lgkmcnt(2)
	v_mfma_f32_16x16x32_bf16 v[124:127], v[114:117], v[152:155], v[124:127]
	s_waitcnt lgkmcnt(1)
	v_mfma_f32_16x16x32_bf16 v[124:127], v[118:121], v[156:159], v[124:127]
	v_lshlrev_b32_e32 v128, 16, v122
	v_and_b32_e32 v129, 0xffff0000, v122
	v_lshlrev_b32_e32 v130, 16, v123
	v_and_b32_e32 v131, 0xffff0000, v123
	s_nop 4
	v_sub_f32_e32 v128, v128, v124
	v_sub_f32_e32 v129, v129, v125
	v_sub_f32_e32 v130, v130, v126
	v_sub_f32_e32 v131, v131, v127
	v_cvt_pk_bf16_f32 v132, v128, v129
	v_cvt_pk_bf16_f32 v133, v130, v131
	ds_write_b64 v13, v[132:133]
	s_waitcnt lgkmcnt(0)
	s_barrier
; __device__ __forceinline__ u32x2 pk4(f32x4 v) { u32x2 r; r.x = pk2(v[0], v[1]); r.y = pk2(v[2], v[3]); return r; }
; __device__ __forceinline__ f32x4 up4(u32x2 u) { return (f32x4){lo16(u.x), hi16(u.x), lo16(u.y), hi16(u.y)}; }
; __device__ __forceinline__ f32x4 mfma16(bf16x8 a, bf16x8 b, f32x4 c) { return __builtin_amdgcn_mfma_f32_16x16x32_bf16(a, b, c, 0, 0, 0); }
; __device__ __forceinline__ void dn_stage_load(DnStage& S, const bf16_t* dW, const bf16_t* dUT, const bf16_t* dKdT, const float* dGl, int ck, int h, int vs, int wave, int r, int q) {
;     const int cc = ck < NCH ? ck : NCH - 1; const size_t ch = (size_t)(cc * 8 + h);
;     if (wave < 4) {
; #pragma unroll
;         for (int kk = 0; kk < 4; ++kk) S.f[kk] = ldfrag(dW + (ch * 64 + wave * 16 + r) * 128 + kk * 32 + q * 8);
;         S.u = *(const u32x2*)(dUT + (ch * 128 + vs * 16 + r) * 64 + wave * 16 + 4 * q);
; __device__ __forceinline__ void dn_step(const DnStage& S, f32x4 (&Sacc)[2], bf16_t* ST, bf16_t* VN, bf16_t* dVnT, bf16_t* dST, int ck, int h, int vs, int wave, int r, int q) {
;     const size_t ch = (size_t)(ck * 8 + h);
;     if (wave < 4) {
;         bf16x8 sf[4];
; #pragma unroll
;         for (int kk = 0; kk < 4; ++kk) sf[kk] = *(const bf16x8*)(ST + r * 136 + kk * 32 + q * 8);
;         f32x4 a = (f32x4){0.f, 0.f, 0.f, 0.f};
; #pragma unroll
;         for (int kk = 0; kk < 4; ++kk) a = mfma16(S.f[kk], sf[kk], a);
;         const f32x4 vn = up4(S.u) - a; const u32x2 pv = pk4(vn);
;         *(u32x2*)(VN + r * 72 + wave * 16 + 4 * q) = pv;
;         *(u32x2*)(dVnT + (ch * 128 + vs * 16 + r) * 64 + wave * 16 + 4 * q) = pv;
;     }
;     asm volatile("s_waitcnt lgkmcnt(0)" ::: "memory"); __builtin_amdgcn_s_barrier(); asm volatile("" ::: "memory");
	global_store_dwordx4 v6, v[136:139], s[6:7]
	s_add_u32 s6, s6, 0x40000
	s_addc_u32 s7, s7, 0
	ds_read_b64 v[140:141], v8
	global_load_dwordx4 v[106:109], v10, s[14:15] offset:0
	global_load_dwordx4 v[110:113], v10, s[14:15] offset:64
	global_load_dwordx4 v[114:117], v10, s[14:15] offset:128
	global_load_dwordx4 v[118:121], v10, s[14:15] offset:192
	global_load_dwordx2 v[122:123], v11, s[16:17]
	s_add_u32 s14, s14, 0x20000
	s_addc_u32 s15, s15, 0
	s_add_u32 s16, s16, 0x20000
	s_addc_u32 s17, s17, 0
	s_waitcnt lgkmcnt(0)
	global_store_dwordx2 v9, v[140:141], s[18:19]
	s_add_u32 s18, s18, 0x20000
	s_addc_u32 s19, s19, 0
	s_barrier
	ds_read_b128 v[144:147], v12 offset:0
	ds_read_b128 v[148:151], v12 offset:64
	ds_read_b128 v[152:155], v12 offset:128
	ds_read_b128 v[156:159], v12 offset:192
	ds_read_b128 v[136:139], v7
	s_waitcnt vmcnt(36)
	s_waitcnt lgkmcnt(4)
	v_mfma_f32_16x16x32_bf16 v[124:127], v[16:19], v[144:147], 0
	s_waitcnt lgkmcnt(3)
	v_mfma_f32_16x16x32_bf16 v[124:127], v[20:23], v[148:151], v[124:127]
	s_waitcnt lgkmcnt(2)
	v_mfma_f32_16x16x32_bf16 v[124:127], v[24:27], v[152:155], v[124:127]
	s_waitcnt lgkmcnt(1)
	v_mfma_f32_16x16x32_bf16 v[124:127], v[28:31], v[156:159], v[124:127]
	v_lshlrev_b32_e32 v128, 16, v32
	v_and_b32_e32 v129, 0xffff0000, v32
	v_lshlrev_b32_e32 v130, 16, v33
	v_and_b32_e32 v131, 0xffff0000, v33
	s_nop 4
	v_sub_f32_e32 v128, v128, v124
	v_sub_f32_e32 v129, v129, v125
	v_sub_f32_e32 v130, v130, v126
	v_sub_f32_e32 v131, v131, v127
	v_cvt_pk_bf16_f32 v132, v128, v129
	v_cvt_pk_bf16_f32 v133, v130, v131
	ds_write_b64 v13, v[132:133]
	s_waitcnt lgkmcnt(0)
	s_barrier
	global_store_dwordx4 v6, v[136:139], s[6:7]
	s_add_u32 s6, s6, 0x40000
	s_addc_u32 s7, s7, 0
	ds_read_b64 v[140:141], v8
	global_load_dwordx4 v[16:19], v10, s[14:15] offset:0
	global_load_dwordx4 v[20:23], v10, s[14:15] offset:64
	global_load_dwordx4 v[24:27], v10, s[14:15] offset:128
	global_load_dwordx4 v[28:31], v10, s[14:15] offset:192
	global_load_dwordx2 v[32:33], v11, s[16:17]
	s_add_u32 s14, s14, 0x20000
	s_addc_u32 s15, s15, 0
	s_add_u32 s16, s16, 0x20000
	s_addc_u32 s17, s17, 0
	s_waitcnt lgkmcnt(0)
	global_store_dwordx2 v9, v[140:141], s[18:19]
	s_add_u32 s18, s18, 0x20000
	s_addc_u32 s19, s19, 0
	s_barrier
	ds_read_b128 v[144:147], v12 offset:0
	ds_read_b128 v[148:151], v12 offset:64
	ds_read_b128 v[152:155], v12 offset:128
	ds_read_b128 v[156:159], v12 offset:192
	ds_read_b128 v[136:139], v7
	s_waitcnt vmcnt(36)
	s_waitcnt lgkmcnt(4)
	v_mfma_f32_16x16x32_bf16 v[124:127], v[34:37], v[144:147], 0
	s_waitcnt lgkmcnt(3)
	v_mfma_f32_16x16x32_bf16 v[124:127], v[38:41], v[148:151], v[124:127]
	s_waitcnt lgkmcnt(2)
	v_mfma_f32_16x16x32_bf16 v[124:127], v[42:45], v[152:155], v[124:127]
	s_waitcnt lgkmcnt(1)
	v_mfma_f32_16x16x32_bf16 v[124:127], v[46:49], v[156:159], v[124:127]
	v_lshlrev_b32_e32 v128, 16, v50
	v_and_b32_e32 v129, 0xffff0000, v50
	v_lshlrev_b32_e32 v130, 16, v51
	v_and_b32_e32 v131, 0xffff0000, v51
	s_nop 4
	v_sub_f32_e32 v128, v128, v124
	v_sub_f32_e32 v129, v129, v125
	v_sub_f32_e32 v130, v130, v126
	v_sub_f32_e32 v131, v131, v127
	v_cvt_pk_bf16_f32 v132, v128, v129
	v_cvt_pk_bf16_f32 v133, v130, v131
	ds_write_b64 v13, v[132:133]
	s_waitcnt lgkmcnt(0)
	s_barrier
	global_store_dwordx4 v6, v[136:139], s[6:7]
	s_add_u32 s6, s6, 0x40000
	s_addc_u32 s7, s7, 0
	ds_read_b64 v[140:141], v8
	global_load_dwordx4 v[34:37], v10, s[14:15] offset:0
	global_load_dwordx4 v[38:41], v10, s[14:15] offset:64
	global_load_dwordx4 v[42:45], v10, s[14:15] offset:128
	global_load_dwordx4 v[46:49], v10, s[14:15] offset:192
	global_load_dwordx2 v[50:51], v11, s[16:17]
	s_add_u32 s14, s14, 0x20000
	s_addc_u32 s15, s15, 0
	s_add_u32 s16, s16, 0x20000
	s_addc_u32 s17, s17, 0
	s_waitcnt lgkmcnt(0)
	global_store_dwordx2 v9, v[140:141], s[18:19]
	s_add_u32 s18, s18, 0x20000
	s_addc_u32 s19, s19, 0
	s_barrier
	s_sub_u32 s20, s20, 1
	s_cmp_lg_u32 s20, 0
	s_cbranch_scc1 .Ldq_A_loop
	ds_read_b128 v[144:147], v12 offset:0
	ds_read_b128 v[148:151], v12 offset:64
	ds_read_b128 v[152:155], v12 offset:128
	ds_read_b128 v[156:159], v12 offset:192
	ds_read_b128 v[136:139], v7
	s_waitcnt vmcnt(36)
	s_waitcnt lgkmcnt(4)
	v_mfma_f32_16x16x32_bf16 v[124:127], v[52:55], v[144:147], 0
	s_waitcnt lgkmcnt(3)
	v_mfma_f32_16x16x32_bf16 v[124:127], v[56:59], v[148:151], v[124:127]
	s_waitcnt lgkmcnt(2)
	v_mfma_f32_16x16x32_bf16 v[124:127], v[60:63], v[152:155], v[124:127]
	s_waitcnt lgkmcnt(1)
	v_mfma_f32_16x16x32_bf16 v[124:127], v[64:67], v[156:159], v[124:127]
	v_lshlrev_b32_e32 v128, 16, v68
	v_and_b32_e32 v129, 0xffff0000, v68
	v_lshlrev_b32_e32 v130, 16, v69
	v_and_b32_e32 v131, 0xffff0000, v69
	s_nop 4
	v_sub_f32_e32 v128, v128, v124
	v_sub_f32_e32 v129, v129, v125
	v_sub_f32_e32 v130, v130, v126
	v_sub_f32_e32 v131, v131, v127
	v_cvt_pk_bf16_f32 v132, v128, v129
	v_cvt_pk_bf16_f32 v133, v130, v131
	ds_write_b64 v13, v[132:133]
	s_waitcnt lgkmcnt(0)
	s_barrier
	global_store_dwordx4 v6, v[136:139], s[6:7]
	s_add_u32 s6, s6, 0x40000
	s_addc_u32 s7, s7, 0
	ds_read_b64 v[140:141], v8
	s_waitcnt lgkmcnt(0)
	global_store_dwordx2 v9, v[140:141], s[18:19]
	s_add_u32 s18, s18, 0x20000
	s_addc_u32 s19, s19, 0
	s_barrier
; __device__ __forceinline__ u32x2 pk4(f32x4 v) { u32x2 r; r.x = pk2(v[0], v[1]); r.y = pk2(v[2], v[3]); return r; }
; __device__ __forceinline__ f32x4 up4(u32x2 u) { return (f32x4){lo16(u.x), hi16(u.x), lo16(u.y), hi16(u.y)}; }
; __device__ __forceinline__ f32x4 mfma16(bf16x8 a, bf16x8 b, f32x4 c) { return __builtin_amdgcn_mfma_f32_16x16x32_bf16(a, b, c, 0, 0, 0); }
; __device__ __forceinline__ void dn_stage_load(DnStage& S, const bf16_t* dW, const bf16_t* dUT, const bf16_t* dKdT, const float* dGl, int ck, int h, int vs, int wave, int r, int q) {
;     const int cc = ck < NCH ? ck : NCH - 1; const size_t ch = (size_t)(cc * 8 + h);
;     if (wave < 4) {
; #pragma unroll
;         for (int kk = 0; kk < 4; ++kk) S.f[kk] = ldfrag(dW + (ch * 64 + wave * 16 + r) * 128 + kk * 32 + q * 8);
;         S.u = *(const u32x2*)(dUT + (ch * 128 + vs * 16 + r) * 64 + wave * 16 + 4 * q);
; __device__ __forceinline__ void dn_step(const DnStage& S, f32x4 (&Sacc)[2], bf16_t* ST, bf16_t* VN, bf16_t* dVnT, bf16_t* dST, int ck, int h, int vs, int wave, int r, int q) {
;     const size_t ch = (size_t)(ck * 8 + h);
;     if (wave < 4) {
;         bf16x8 sf[4];
; #pragma unroll
;         for (int kk = 0; kk < 4; ++kk) sf[kk] = *(const bf16x8*)(ST + r * 136 + kk * 32 + q * 8);
;         f32x4 a = (f32x4){0.f, 0.f, 0.f, 0.f};
; #pragma unroll
;         for (int kk = 0; kk < 4; ++kk) a = mfma16(S.f[kk], sf[kk], a);
;         const f32x4 vn = up4(S.u) - a; const u32x2 pv = pk4(vn);
;         *(u32x2*)(VN + r * 72 + wave * 16 + 4 * q) = pv;
;         *(u32x2*)(dVnT + (ch * 128 + vs * 16 + r) * 64 + wave * 16 + 4 * q) = pv;
;     }
;     asm volatile("s_waitcnt lgkmcnt(0)" ::: "memory"); __builtin_amdgcn_s_barrier(); asm volatile("" ::: "memory");
	ds_read_b128 v[144:147], v12 offset:0
	ds_read_b128 v[148:151], v12 offset:64
	ds_read_b128 v[152:155], v12 offset:128
	ds_read_b128 v[156:159], v12 offset:192
	ds_read_b128 v[136:139], v7
	s_waitcnt vmcnt(31)
	s_waitcnt lgkmcnt(4)
	v_mfma_f32_16x16x32_bf16 v[124:127], v[70:73], v[144:147], 0
	s_waitcnt lgkmcnt(3)
	v_mfma_f32_16x16x32_bf16 v[124:127], v[74:77], v[148:151], v[124:127]
	s_waitcnt lgkmcnt(2)
	v_mfma_f32_16x16x32_bf16 v[124:127], v[78:81], v[152:155], v[124:127]
	s_waitcnt lgkmcnt(1)
	v_mfma_f32_16x16x32_bf16 v[124:127], v[82:85], v[156:159], v[124:127]
	v_lshlrev_b32_e32 v128, 16, v86
	v_and_b32_e32 v129, 0xffff0000, v86
	v_lshlrev_b32_e32 v130, 16, v87
	v_and_b32_e32 v131, 0xffff0000, v87
	s_nop 4
	v_sub_f32_e32 v128, v128, v124
	v_sub_f32_e32 v129, v129, v125
	v_sub_f32_e32 v130, v130, v126
	v_sub_f32_e32 v131, v131, v127
	v_cvt_pk_bf16_f32 v132, v128, v129
	v_cvt_pk_bf16_f32 v133, v130, v131
	ds_write_b64 v13, v[132:133]
	s_waitcnt lgkmcnt(0)
	s_barrier
	global_store_dwordx4 v6, v[136:139], s[6:7]
	s_add_u32 s6, s6, 0x40000
	s_addc_u32 s7, s7, 0
	ds_read_b64 v[140:141], v8
	s_waitcnt lgkmcnt(0)
	global_store_dwordx2 v9, v[140:141], s[18:19]
	s_add_u32 s18, s18, 0x20000
	s_addc_u32 s19, s19, 0
	s_barrier
	ds_read_b128 v[144:147], v12 offset:0
	ds_read_b128 v[148:151], v12 offset:64
	ds_read_b128 v[152:155], v12 offset:128
	ds_read_b128 v[156:159], v12 offset:192
	ds_read_b128 v[136:139], v7
	s_waitcnt vmcnt(26)
	s_waitcnt lgkmcnt(4)
	v_mfma_f32_16x16x32_bf16 v[124:127], v[88:91], v[144:147], 0
	s_waitcnt lgkmcnt(3)
	v_mfma_f32_16x16x32_bf16 v[124:127], v[92:95], v[148:151], v[124:127]
	s_waitcnt lgkmcnt(2)
	v_mfma_f32_16x16x32_bf16 v[124:127], v[96:99], v[152:155], v[124:127]
	s_waitcnt lgkmcnt(1)
	v_mfma_f32_16x16x32_bf16 v[124:127], v[100:103], v[156:159], v[124:127]
	v_lshlrev_b32_e32 v128, 16, v104
	v_and_b32_e32 v129, 0xffff0000, v104
	v_lshlrev_b32_e32 v130, 16, v105
	v_and_b32_e32 v131, 0xffff0000, v105
	s_nop 4
	v_sub_f32_e32 v128, v128, v124
	v_sub_f32_e32 v129, v129, v125
	v_sub_f32_e32 v130, v130, v126
	v_sub_f32_e32 v131, v131, v127
	v_cvt_pk_bf16_f32 v132, v128, v129
	v_cvt_pk_bf16_f32 v133, v130, v131
	ds_write_b64 v13, v[132:133]
	s_waitcnt lgkmcnt(0)
	s_barrier
	global_store_dwordx4 v6, v[136:139], s[6:7]
	s_add_u32 s6, s6, 0x40000
	s_addc_u32 s7, s7, 0
	ds_read_b64 v[140:141], v8
	s_waitcnt lgkmcnt(0)
	global_store_dwordx2 v9, v[140:141], s[18:19]
	s_add_u32 s18, s18, 0x20000
	s_addc_u32 s19, s19, 0
	s_barrier
	ds_read_b128 v[144:147], v12 offset:0
	ds_read_b128 v[148:151], v12 offset:64
	ds_read_b128 v[152:155], v12 offset:128
	ds_read_b128 v[156:159], v12 offset:192
	ds_read_b128 v[136:139], v7
	s_waitcnt vmcnt(21)
	s_waitcnt lgkmcnt(4)
	v_mfma_f32_16x16x32_bf16 v[124:127], v[106:109], v[144:147], 0
	s_waitcnt lgkmcnt(3)
	v_mfma_f32_16x16x32_bf16 v[124:127], v[110:113], v[148:151], v[124:127]
	s_waitcnt lgkmcnt(2)
	v_mfma_f32_16x16x32_bf16 v[124:127], v[114:117], v[152:155], v[124:127]
	s_waitcnt lgkmcnt(1)
	v_mfma_f32_16x16x32_bf16 v[124:127], v[118:121], v[156:159], v[124:127]
	v_lshlrev_b32_e32 v128, 16, v122
	v_and_b32_e32 v129, 0xffff0000, v122
	v_lshlrev_b32_e32 v130, 16, v123
	v_and_b32_e32 v131, 0xffff0000, v123
	s_nop 4
	v_sub_f32_e32 v128, v128, v124
	v_sub_f32_e32 v129, v129, v125
	v_sub_f32_e32 v130, v130, v126
	v_sub_f32_e32 v131, v131, v127
	v_cvt_pk_bf16_f32 v132, v128, v129
	v_cvt_pk_bf16_f32 v133, v130, v131
	ds_write_b64 v13, v[132:133]
	s_waitcnt lgkmcnt(0)
	s_barrier
	global_store_dwordx4 v6, v[136:139], s[6:7]
	s_add_u32 s6, s6, 0x40000
	s_addc_u32 s7, s7, 0
	ds_read_b64 v[140:141], v8
	s_waitcnt lgkmcnt(0)
	global_store_dwordx2 v9, v[140:141], s[18:19]
	s_add_u32 s18, s18, 0x20000
	s_addc_u32 s19, s19, 0
	s_barrier
	ds_read_b128 v[144:147], v12 offset:0
	ds_read_b128 v[148:151], v12 offset:64
	ds_read_b128 v[152:155], v12 offset:128
	ds_read_b128 v[156:159], v12 offset:192
	ds_read_b128 v[136:139], v7
	s_waitcnt vmcnt(16)
	s_waitcnt lgkmcnt(4)
	v_mfma_f32_16x16x32_bf16 v[124:127], v[16:19], v[144:147], 0
	s_waitcnt lgkmcnt(3)
	v_mfma_f32_16x16x32_bf16 v[124:127], v[20:23], v[148:151], v[124:127]
	s_waitcnt lgkmcnt(2)
	v_mfma_f32_16x16x32_bf16 v[124:127], v[24:27], v[152:155], v[124:127]
	s_waitcnt lgkmcnt(1)
	v_mfma_f32_16x16x32_bf16 v[124:127], v[28:31], v[156:159], v[124:127]
	v_lshlrev_b32_e32 v128, 16, v32
	v_and_b32_e32 v129, 0xffff0000, v32
	v_lshlrev_b32_e32 v130, 16, v33
	v_and_b32_e32 v131, 0xffff0000, v33
	s_nop 4
	v_sub_f32_e32 v128, v128, v124
	v_sub_f32_e32 v129, v129, v125
	v_sub_f32_e32 v130, v130, v126
	v_sub_f32_e32 v131, v131, v127
	v_cvt_pk_bf16_f32 v132, v128, v129
	v_cvt_pk_bf16_f32 v133, v130, v131
	ds_write_b64 v13, v[132:133]
	s_waitcnt lgkmcnt(0)
	s_barrier
	global_store_dwordx4 v6, v[136:139], s[6:7]
	s_add_u32 s6, s6, 0x40000
	s_addc_u32 s7, s7, 0
	ds_read_b64 v[140:141], v8
	s_waitcnt lgkmcnt(0)
	global_store_dwordx2 v9, v[140:141], s[18:19]
	s_add_u32 s18, s18, 0x20000
	s_addc_u32 s19, s19, 0
	s_barrier
	ds_read_b128 v[144:147], v12 offset:0
	ds_read_b128 v[148:151], v12 offset:64
	ds_read_b128 v[152:155], v12 offset:128
	ds_read_b128 v[156:159], v12 offset:192
	ds_read_b128 v[136:139], v7
	s_waitcnt vmcnt(11)
	s_waitcnt lgkmcnt(4)
	v_mfma_f32_16x16x32_bf16 v[124:127], v[34:37], v[144:147], 0
	s_waitcnt lgkmcnt(3)
	v_mfma_f32_16x16x32_bf16 v[124:127], v[38:41], v[148:151], v[124:127]
	s_waitcnt lgkmcnt(2)
	v_mfma_f32_16x16x32_bf16 v[124:127], v[42:45], v[152:155], v[124:127]
	s_waitcnt lgkmcnt(1)
	v_mfma_f32_16x16x32_bf16 v[124:127], v[46:49], v[156:159], v[124:127]
	v_lshlrev_b32_e32 v128, 16, v50
	v_and_b32_e32 v129, 0xffff0000, v50
	v_lshlrev_b32_e32 v130, 16, v51
	v_and_b32_e32 v131, 0xffff0000, v51
	s_nop 4
	v_sub_f32_e32 v128, v128, v124
	v_sub_f32_e32 v129, v129, v125
	v_sub_f32_e32 v130, v130, v126
	v_sub_f32_e32 v131, v131, v127
	v_cvt_pk_bf16_f32 v132, v128, v129
	v_cvt_pk_bf16_f32 v133, v130, v131
	ds_write_b64 v13, v[132:133]
	s_waitcnt lgkmcnt(0)
	s_barrier
	global_store_dwordx4 v6, v[136:139], s[6:7]
	s_add_u32 s6, s6, 0x40000
	s_addc_u32 s7, s7, 0
	ds_read_b64 v[140:141], v8
	s_waitcnt lgkmcnt(0)
	global_store_dwordx2 v9, v[140:141], s[18:19]
	s_add_u32 s18, s18, 0x20000
	s_addc_u32 s19, s19, 0
	s_barrier
	s_branch .Ldq_done
; __device__ __forceinline__ u32x2 pk4(f32x4 v) { u32x2 r; r.x = pk2(v[0], v[1]); r.y = pk2(v[2], v[3]); return r; }
; __device__ __forceinline__ f32x4 mfma16(bf16x8 a, bf16x8 b, f32x4 c) { return __builtin_amdgcn_mfma_f32_16x16x32_bf16(a, b, c, 0, 0, 0); }
; __device__ __forceinline__ void dn_stage_load(DnStage& S, const bf16_t* dW, const bf16_t* dUT, const bf16_t* dKdT, const float* dGl, int ck, int h, int vs, int wave, int r, int q) {
;     ...
; #pragma unroll
;         for (int t = 0; t < 2; ++t)
; #pragma unroll
;             for (int kk = 0; kk < 2; ++kk) S.f[t * 2 + kk] = ldfrag(dKdT + (ch * 128 + ((wave - 4) * 2 + t) * 16 + r) * 64 + kk * 32 + q * 8);
;         S.gl = dGl[ch];
; __device__ __forceinline__ void dn_step(const DnStage& S, f32x4 (&Sacc)[2], bf16_t* ST, bf16_t* VN, bf16_t* dVnT, bf16_t* dST, int ck, int h, int vs, int wave, int r, int q) {
;     ...
;     if (wave >= 4) {
;         bf16x8 vf[2];
; #pragma unroll
;         for (int kk = 0; kk < 2; ++kk) vf[kk] = *(const bf16x8*)(VN + r * 72 + kk * 32 + q * 8);
; #pragma unroll
;         for (int t = 0; t < 2; ++t) { const int kb = (wave - 4) * 2 + t;
;             f32x4 a = Sacc[t] * S.gl;
; #pragma unroll
;             for (int kk = 0; kk < 2; ++kk) a = mfma16(S.f[t * 2 + kk], vf[kk], a);
;             Sacc[t] = a; const u32x2 ps = pk4(a);
;             *(u32x2*)(ST + r * 136 + kb * 16 + 4 * q) = ps;
;             if (ck + 1 < NCH) *(u32x2*)(dST + (((size_t)(ck + 1) * 8 + h) * 128 + vs * 16 + r) * 128 + kb * 16 + 4 * q) = ps; }
;     }
;     asm volatile("s_waitcnt lgkmcnt(0)" ::: "memory"); __builtin_amdgcn_s_barrier(); asm volatile("" ::: "memory");
; __device__ void dn_seq(const Ctx& c, int h, int vs) {
;     ...
;     f32x4 Sacc[2]; Sacc[0] = (f32x4){0.f, 0.f, 0.f, 0.f}; Sacc[1] = Sacc[0];
;     __syncthreads();
;     { u32x2 z; z.x = 0u; z.y = 0u; *(u32x2*)(ST + r * 136 + wave * 16 + 4 * q) = z;
;       *(u32x2*)(dST + ((size_t)h * 128 + vs * 16 + r) * 128 + wave * 16 + 4 * q) = z; }
;     __syncthreads();
.Ldq_B:
	s_sub_u32 s0, s22, 4
	s_lshl_b32 s1, s0, 5
	v_add_u32_e32 v10, s1, v1
	v_lshlrev_b32_e32 v10, 7, v10
	v_lshl_add_u32 v10, v2, 4, v10
	v_and_b32_e32 v0, 63, v234
	v_lshlrev_b32_e32 v11, 5, v0
	v_mul_u32_u24_e32 v12, 0x90, v1
	v_lshl_add_u32 v12, v2, 4, v12
	v_add_u32_e32 v12, 0x1100, v12
	s_lshl_b32 s1, s0, 6
	v_add_u32_e32 v13, s1, v4
	v_lshl_add_u32 v13, v2, 3, v3
	v_add_u32_e32 v13, s1, v13
	v_add_u32_e32 v14, s1, v6
	s_add_u32 s14, s4, 0x24100000
	s_addc_u32 s15, s5, 0
	s_add_u32 s14, s14, s3
	s_addc_u32 s15, s15, 0
	s_lshl_b32 s1, s11, 2
	s_add_u32 s16, s4, 0x29900000
	s_addc_u32 s17, s5, 0
	s_add_u32 s16, s16, s1
	s_addc_u32 s17, s17, 0
	v_mov_b32_e32 v128, 0
	v_mov_b32_e32 v129, 0
	v_mov_b32_e32 v130, 0
	v_mov_b32_e32 v131, 0
	v_mov_b32_e32 v132, 0
	v_mov_b32_e32 v133, 0
	v_mov_b32_e32 v134, 0
	v_mov_b32_e32 v135, 0
	global_load_dword v152, v11, s[16:17]
	global_load_dword v153, v11, s[16:17] offset:2048
	s_mov_b32 s41, 0
	global_load_dwordx4 v[16:19], v10, s[14:15] offset:0
	global_load_dwordx4 v[20:23], v10, s[14:15] offset:64
	global_load_dwordx4 v[24:27], v10, s[14:15] offset:2048
	global_load_dwordx4 v[28:31], v10, s[14:15] offset:2112
	s_add_u32 s14, s14, 0x20000
	s_addc_u32 s15, s15, 0
	global_load_dwordx4 v[34:37], v10, s[14:15] offset:0
	global_load_dwordx4 v[38:41], v10, s[14:15] offset:64
	global_load_dwordx4 v[42:45], v10, s[14:15] offset:2048
	global_load_dwordx4 v[46:49], v10, s[14:15] offset:2112
	s_add_u32 s14, s14, 0x20000
	s_addc_u32 s15, s15, 0
	global_load_dwordx4 v[52:55], v10, s[14:15] offset:0
	global_load_dwordx4 v[56:59], v10, s[14:15] offset:64
	global_load_dwordx4 v[60:63], v10, s[14:15] offset:2048
	global_load_dwordx4 v[64:67], v10, s[14:15] offset:2112
	s_add_u32 s14, s14, 0x20000
	s_addc_u32 s15, s15, 0
	global_load_dwordx4 v[70:73], v10, s[14:15] offset:0
	global_load_dwordx4 v[74:77], v10, s[14:15] offset:64
	global_load_dwordx4 v[78:81], v10, s[14:15] offset:2048
	global_load_dwordx4 v[82:85], v10, s[14:15] offset:2112
	s_add_u32 s14, s14, 0x20000
	s_addc_u32 s15, s15, 0
	global_load_dwordx4 v[88:91], v10, s[14:15] offset:0
	global_load_dwordx4 v[92:95], v10, s[14:15] offset:64
	global_load_dwordx4 v[96:99], v10, s[14:15] offset:2048
	global_load_dwordx4 v[100:103], v10, s[14:15] offset:2112
	s_add_u32 s14, s14, 0x20000
	s_addc_u32 s15, s15, 0
	global_load_dwordx4 v[106:109], v10, s[14:15] offset:0
	global_load_dwordx4 v[110:113], v10, s[14:15] offset:64
	global_load_dwordx4 v[114:117], v10, s[14:15] offset:2048
	global_load_dwordx4 v[118:121], v10, s[14:15] offset:2112
	s_add_u32 s14, s14, 0x20000
	s_addc_u32 s15, s15, 0
	s_waitcnt vmcnt(20)
	v_readlane_b32 s40, v152, 0
	s_nop 1
	v_mul_f32_e32 v128, s40, v128
	v_mul_f32_e32 v129, s40, v129
	v_mul_f32_e32 v130, s40, v130
	v_mul_f32_e32 v131, s40, v131
	v_mul_f32_e32 v132, s40, v132
	v_mul_f32_e32 v133, s40, v133
	v_mul_f32_e32 v134, s40, v134
	v_mul_f32_e32 v135, s40, v135
	s_barrier
	ds_read_b128 v[144:147], v12
	ds_read_b128 v[148:151], v12 offset:64
	s_waitcnt lgkmcnt(1)
	v_mfma_f32_16x16x32_bf16 v[128:131], v[16:19], v[144:147], v[128:131]
	v_mfma_f32_16x16x32_bf16 v[132:135], v[24:27], v[144:147], v[132:135]
	s_waitcnt lgkmcnt(0)
	v_mfma_f32_16x16x32_bf16 v[128:131], v[20:23], v[148:151], v[128:131]
	v_mfma_f32_16x16x32_bf16 v[132:135], v[28:31], v[148:151], v[132:135]
	s_nop 7
	v_cvt_pk_bf16_f32 v136, v128, v129
	v_cvt_pk_bf16_f32 v137, v130, v131
	s_nop 1
	v_cvt_pk_bf16_f32 v138, v132, v133
	v_cvt_pk_bf16_f32 v139, v134, v135
	ds_write_b64 v13, v[136:137]
	ds_write_b64 v13, v[138:139] offset:32
	s_waitcnt lgkmcnt(0)
	s_barrier
	global_load_dwordx4 v[16:19], v10, s[14:15] offset:0
	global_load_dwordx4 v[20:23], v10, s[14:15] offset:64
	global_load_dwordx4 v[24:27], v10, s[14:15] offset:2048
	global_load_dwordx4 v[28:31], v10, s[14:15] offset:2112
	s_add_u32 s14, s14, 0x20000
	s_addc_u32 s15, s15, 0
	s_waitcnt vmcnt(20)
	v_readlane_b32 s40, v152, 1
	s_nop 1
	v_mul_f32_e32 v128, s40, v128
	v_mul_f32_e32 v129, s40, v129
	v_mul_f32_e32 v130, s40, v130
	v_mul_f32_e32 v131, s40, v131
	v_mul_f32_e32 v132, s40, v132
	v_mul_f32_e32 v133, s40, v133
	v_mul_f32_e32 v134, s40, v134
	v_mul_f32_e32 v135, s40, v135
	s_barrier
	ds_read_b128 v[144:147], v12
	ds_read_b128 v[148:151], v12 offset:64
	s_waitcnt lgkmcnt(1)
	v_mfma_f32_16x16x32_bf16 v[128:131], v[34:37], v[144:147], v[128:131]
	v_mfma_f32_16x16x32_bf16 v[132:135], v[42:45], v[144:147], v[132:135]
	s_waitcnt lgkmcnt(0)
	v_mfma_f32_16x16x32_bf16 v[128:131], v[38:41], v[148:151], v[128:131]
	v_mfma_f32_16x16x32_bf16 v[132:135], v[46:49], v[148:151], v[132:135]
	s_nop 7
	v_cvt_pk_bf16_f32 v136, v128, v129
	v_cvt_pk_bf16_f32 v137, v130, v131
	s_nop 1
	v_cvt_pk_bf16_f32 v138, v132, v133
	v_cvt_pk_bf16_f32 v139, v134, v135
	ds_write_b64 v13, v[136:137]
	ds_write_b64 v13, v[138:139] offset:32
	s_waitcnt lgkmcnt(0)
	s_barrier
	global_load_dwordx4 v[34:37], v10, s[14:15] offset:0
	global_load_dwordx4 v[38:41], v10, s[14:15] offset:64
	global_load_dwordx4 v[42:45], v10, s[14:15] offset:2048
	global_load_dwordx4 v[46:49], v10, s[14:15] offset:2112
	s_add_u32 s14, s14, 0x20000
	s_addc_u32 s15, s15, 0
	s_waitcnt vmcnt(20)
	v_readlane_b32 s40, v152, 2
	s_nop 1
	v_mul_f32_e32 v128, s40, v128
	v_mul_f32_e32 v129, s40, v129
	v_mul_f32_e32 v130, s40, v130
	v_mul_f32_e32 v131, s40, v131
	v_mul_f32_e32 v132, s40, v132
	v_mul_f32_e32 v133, s40, v133
	v_mul_f32_e32 v134, s40, v134
	v_mul_f32_e32 v135, s40, v135
	s_barrier
; __device__ __forceinline__ u32x2 pk4(f32x4 v) { u32x2 r; r.x = pk2(v[0], v[1]); r.y = pk2(v[2], v[3]); return r; }
; __device__ __forceinline__ f32x4 mfma16(bf16x8 a, bf16x8 b, f32x4 c) { return __builtin_amdgcn_mfma_f32_16x16x32_bf16(a, b, c, 0, 0, 0); }
; __device__ __forceinline__ void dn_stage_load(DnStage& S, const bf16_t* dW, const bf16_t* dUT, const bf16_t* dKdT, const float* dGl, int ck, int h, int vs, int wave, int r, int q) {
;     ...
; #pragma unroll
;         for (int t = 0; t < 2; ++t)
; #pragma unroll
;             for (int kk = 0; kk < 2; ++kk) S.f[t * 2 + kk] = ldfrag(dKdT + (ch * 128 + ((wave - 4) * 2 + t) * 16 + r) * 64 + kk * 32 + q * 8);
;         S.gl = dGl[ch];
; __device__ __forceinline__ void dn_step(const DnStage& S, f32x4 (&Sacc)[2], bf16_t* ST, bf16_t* VN, bf16_t* dVnT, bf16_t* dST, int ck, int h, int vs, int wave, int r, int q) {
;     ...
;     if (wave >= 4) {
;         bf16x8 vf[2];
; #pragma unroll
;         for (int kk = 0; kk < 2; ++kk) vf[kk] = *(const bf16x8*)(VN + r * 72 + kk * 32 + q * 8);
; #pragma unroll
;         for (int t = 0; t < 2; ++t) { const int kb = (wave - 4) * 2 + t;
;             f32x4 a = Sacc[t] * S.gl;
; #pragma unroll
;             for (int kk = 0; kk < 2; ++kk) a = mfma16(S.f[t * 2 + kk], vf[kk], a);
;             Sacc[t] = a; const u32x2 ps = pk4(a);
;             *(u32x2*)(ST + r * 136 + kb * 16 + 4 * q) = ps;
;             if (ck + 1 < NCH) *(u32x2*)(dST + (((size_t)(ck + 1) * 8 + h) * 128 + vs * 16 + r) * 128 + kb * 16 + 4 * q) = ps; }
;     }
;     asm volatile("s_waitcnt lgkmcnt(0)" ::: "memory"); __builtin_amdgcn_s_barrier(); asm volatile("" ::: "memory");
	ds_read_b128 v[144:147], v12
	ds_read_b128 v[148:151], v12 offset:64
	s_waitcnt lgkmcnt(1)
	v_mfma_f32_16x16x32_bf16 v[128:131], v[52:55], v[144:147], v[128:131]
	v_mfma_f32_16x16x32_bf16 v[132:135], v[60:63], v[144:147], v[132:135]
	s_waitcnt lgkmcnt(0)
	v_mfma_f32_16x16x32_bf16 v[128:131], v[56:59], v[148:151], v[128:131]
	v_mfma_f32_16x16x32_bf16 v[132:135], v[64:67], v[148:151], v[132:135]
	s_nop 7
	v_cvt_pk_bf16_f32 v136, v128, v129
	v_cvt_pk_bf16_f32 v137, v130, v131
	s_nop 1
	v_cvt_pk_bf16_f32 v138, v132, v133
	v_cvt_pk_bf16_f32 v139, v134, v135
	ds_write_b64 v13, v[136:137]
	ds_write_b64 v13, v[138:139] offset:32
	s_waitcnt lgkmcnt(0)
	s_barrier
	global_load_dwordx4 v[52:55], v10, s[14:15] offset:0
	global_load_dwordx4 v[56:59], v10, s[14:15] offset:64
	global_load_dwordx4 v[60:63], v10, s[14:15] offset:2048
	global_load_dwordx4 v[64:67], v10, s[14:15] offset:2112
	s_add_u32 s14, s14, 0x20000
	s_addc_u32 s15, s15, 0
	s_waitcnt vmcnt(20)
	v_readlane_b32 s40, v152, 3
	s_nop 1
	v_mul_f32_e32 v128, s40, v128
	v_mul_f32_e32 v129, s40, v129
	v_mul_f32_e32 v130, s40, v130
	v_mul_f32_e32 v131, s40, v131
	v_mul_f32_e32 v132, s40, v132
	v_mul_f32_e32 v133, s40, v133
	v_mul_f32_e32 v134, s40, v134
	v_mul_f32_e32 v135, s40, v135
	s_barrier
	ds_read_b128 v[144:147], v12
	ds_read_b128 v[148:151], v12 offset:64
	s_waitcnt lgkmcnt(1)
	v_mfma_f32_16x16x32_bf16 v[128:131], v[70:73], v[144:147], v[128:131]
	v_mfma_f32_16x16x32_bf16 v[132:135], v[78:81], v[144:147], v[132:135]
	s_waitcnt lgkmcnt(0)
	v_mfma_f32_16x16x32_bf16 v[128:131], v[74:77], v[148:151], v[128:131]
	v_mfma_f32_16x16x32_bf16 v[132:135], v[82:85], v[148:151], v[132:135]
	s_nop 7
	v_cvt_pk_bf16_f32 v136, v128, v129
	v_cvt_pk_bf16_f32 v137, v130, v131
	s_nop 1
	v_cvt_pk_bf16_f32 v138, v132, v133
	v_cvt_pk_bf16_f32 v139, v134, v135
	ds_write_b64 v13, v[136:137]
	ds_write_b64 v13, v[138:139] offset:32
	s_waitcnt lgkmcnt(0)
	s_barrier
	global_load_dwordx4 v[70:73], v10, s[14:15] offset:0
	global_load_dwordx4 v[74:77], v10, s[14:15] offset:64
	global_load_dwordx4 v[78:81], v10, s[14:15] offset:2048
	global_load_dwordx4 v[82:85], v10, s[14:15] offset:2112
	s_add_u32 s14, s14, 0x20000
	s_addc_u32 s15, s15, 0
	s_waitcnt vmcnt(20)
	v_readlane_b32 s40, v152, 4
	s_nop 1
	v_mul_f32_e32 v128, s40, v128
	v_mul_f32_e32 v129, s40, v129
	v_mul_f32_e32 v130, s40, v130
	v_mul_f32_e32 v131, s40, v131
	v_mul_f32_e32 v132, s40, v132
	v_mul_f32_e32 v133, s40, v133
	v_mul_f32_e32 v134, s40, v134
	v_mul_f32_e32 v135, s40, v135
	s_barrier
	ds_read_b128 v[144:147], v12
	ds_read_b128 v[148:151], v12 offset:64
	s_waitcnt lgkmcnt(1)
	v_mfma_f32_16x16x32_bf16 v[128:131], v[88:91], v[144:147], v[128:131]
	v_mfma_f32_16x16x32_bf16 v[132:135], v[96:99], v[144:147], v[132:135]
	s_waitcnt lgkmcnt(0)
	v_mfma_f32_16x16x32_bf16 v[128:131], v[92:95], v[148:151], v[128:131]
	v_mfma_f32_16x16x32_bf16 v[132:135], v[100:103], v[148:151], v[132:135]
	s_nop 7
	v_cvt_pk_bf16_f32 v136, v128, v129
	v_cvt_pk_bf16_f32 v137, v130, v131
	s_nop 1
	v_cvt_pk_bf16_f32 v138, v132, v133
	v_cvt_pk_bf16_f32 v139, v134, v135
	ds_write_b64 v13, v[136:137]
	ds_write_b64 v13, v[138:139] offset:32
	s_waitcnt lgkmcnt(0)
	s_barrier
	global_load_dwordx4 v[88:91], v10, s[14:15] offset:0
	global_load_dwordx4 v[92:95], v10, s[14:15] offset:64
	global_load_dwordx4 v[96:99], v10, s[14:15] offset:2048
	global_load_dwordx4 v[100:103], v10, s[14:15] offset:2112
	s_add_u32 s14, s14, 0x20000
	s_addc_u32 s15, s15, 0
	s_waitcnt vmcnt(20)
	v_readlane_b32 s40, v152, 5
	s_nop 1
	v_mul_f32_e32 v128, s40, v128
	v_mul_f32_e32 v129, s40, v129
	v_mul_f32_e32 v130, s40, v130
	v_mul_f32_e32 v131, s40, v131
	v_mul_f32_e32 v132, s40, v132
	v_mul_f32_e32 v133, s40, v133
	v_mul_f32_e32 v134, s40, v134
	v_mul_f32_e32 v135, s40, v135
	s_barrier
	ds_read_b128 v[144:147], v12
	ds_read_b128 v[148:151], v12 offset:64
	s_waitcnt lgkmcnt(1)
	v_mfma_f32_16x16x32_bf16 v[128:131], v[106:109], v[144:147], v[128:131]
	v_mfma_f32_16x16x32_bf16 v[132:135], v[114:117], v[144:147], v[132:135]
	s_waitcnt lgkmcnt(0)
	v_mfma_f32_16x16x32_bf16 v[128:131], v[110:113], v[148:151], v[128:131]
	v_mfma_f32_16x16x32_bf16 v[132:135], v[118:121], v[148:151], v[132:135]
	s_nop 7
	v_cvt_pk_bf16_f32 v136, v128, v129
	v_cvt_pk_bf16_f32 v137, v130, v131
	s_nop 1
	v_cvt_pk_bf16_f32 v138, v132, v133
	v_cvt_pk_bf16_f32 v139, v134, v135
	ds_write_b64 v13, v[136:137]
	ds_write_b64 v13, v[138:139] offset:32
	s_waitcnt lgkmcnt(0)
	s_barrier
	global_load_dwordx4 v[106:109], v10, s[14:15] offset:0
	global_load_dwordx4 v[110:113], v10, s[14:15] offset:64
	global_load_dwordx4 v[114:117], v10, s[14:15] offset:2048
	global_load_dwordx4 v[118:121], v10, s[14:15] offset:2112
	s_add_u32 s14, s14, 0x20000
	s_addc_u32 s15, s15, 0
	s_waitcnt vmcnt(20)
	v_readlane_b32 s40, v152, 6
	s_nop 1
	v_mul_f32_e32 v128, s40, v128
	v_mul_f32_e32 v129, s40, v129
	v_mul_f32_e32 v130, s40, v130
	v_mul_f32_e32 v131, s40, v131
	v_mul_f32_e32 v132, s40, v132
	v_mul_f32_e32 v133, s40, v133
	v_mul_f32_e32 v134, s40, v134
	v_mul_f32_e32 v135, s40, v135
	s_barrier
	ds_read_b128 v[144:147], v12
	ds_read_b128 v[148:151], v12 offset:64
	s_waitcnt lgkmcnt(1)
	v_mfma_f32_16x16x32_bf16 v[128:131], v[16:19], v[144:147], v[128:131]
	v_mfma_f32_16x16x32_bf16 v[132:135], v[24:27], v[144:147], v[132:135]
	s_waitcnt lgkmcnt(0)
	v_mfma_f32_16x16x32_bf16 v[128:131], v[20:23], v[148:151], v[128:131]
	v_mfma_f32_16x16x32_bf16 v[132:135], v[28:31], v[148:151], v[132:135]
	s_nop 7
	v_cvt_pk_bf16_f32 v136, v128, v129
	v_cvt_pk_bf16_f32 v137, v130, v131
	s_nop 1
	v_cvt_pk_bf16_f32 v138, v132, v133
	v_cvt_pk_bf16_f32 v139, v134, v135
	ds_write_b64 v13, v[136:137]
	ds_write_b64 v13, v[138:139] offset:32
	s_waitcnt lgkmcnt(0)
	s_barrier
	global_load_dwordx4 v[16:19], v10, s[14:15] offset:0
	global_load_dwordx4 v[20:23], v10, s[14:15] offset:64
	global_load_dwordx4 v[24:27], v10, s[14:15] offset:2048
	global_load_dwordx4 v[28:31], v10, s[14:15] offset:2112
	s_add_u32 s14, s14, 0x20000
	s_addc_u32 s15, s15, 0
	s_waitcnt vmcnt(20)
	v_readlane_b32 s40, v152, 7
	s_nop 1
	v_mul_f32_e32 v128, s40, v128
	v_mul_f32_e32 v129, s40, v129
	v_mul_f32_e32 v130, s40, v130
	v_mul_f32_e32 v131, s40, v131
	v_mul_f32_e32 v132, s40, v132
	v_mul_f32_e32 v133, s40, v133
	v_mul_f32_e32 v134, s40, v134
	v_mul_f32_e32 v135, s40, v135
	s_barrier
	ds_read_b128 v[144:147], v12
	ds_read_b128 v[148:151], v12 offset:64
	s_waitcnt lgkmcnt(1)
	v_mfma_f32_16x16x32_bf16 v[128:131], v[34:37], v[144:147], v[128:131]
	v_mfma_f32_16x16x32_bf16 v[132:135], v[42:45], v[144:147], v[132:135]
	s_waitcnt lgkmcnt(0)
	v_mfma_f32_16x16x32_bf16 v[128:131], v[38:41], v[148:151], v[128:131]
	v_mfma_f32_16x16x32_bf16 v[132:135], v[46:49], v[148:151], v[132:135]
	s_nop 7
	v_cvt_pk_bf16_f32 v136, v128, v129
	v_cvt_pk_bf16_f32 v137, v130, v131
	s_nop 1
	v_cvt_pk_bf16_f32 v138, v132, v133
	v_cvt_pk_bf16_f32 v139, v134, v135
	ds_write_b64 v13, v[136:137]
	ds_write_b64 v13, v[138:139] offset:32
	s_waitcnt lgkmcnt(0)
	s_barrier
	s_mov_b32 s20, 19
	s_mov_b32 s41, 8
; __device__ __forceinline__ u32x2 pk4(f32x4 v) { u32x2 r; r.x = pk2(v[0], v[1]); r.y = pk2(v[2], v[3]); return r; }
; __device__ __forceinline__ f32x4 mfma16(bf16x8 a, bf16x8 b, f32x4 c) { return __builtin_amdgcn_mfma_f32_16x16x32_bf16(a, b, c, 0, 0, 0); }
; __device__ __forceinline__ void dn_stage_load(DnStage& S, const bf16_t* dW, const bf16_t* dUT, const bf16_t* dKdT, const float* dGl, int ck, int h, int vs, int wave, int r, int q) {
;     ...
; #pragma unroll
;         for (int t = 0; t < 2; ++t)
; #pragma unroll
;             for (int kk = 0; kk < 2; ++kk) S.f[t * 2 + kk] = ldfrag(dKdT + (ch * 128 + ((wave - 4) * 2 + t) * 16 + r) * 64 + kk * 32 + q * 8);
;         S.gl = dGl[ch];
; __device__ __forceinline__ void dn_step(const DnStage& S, f32x4 (&Sacc)[2], bf16_t* ST, bf16_t* VN, bf16_t* dVnT, bf16_t* dST, int ck, int h, int vs, int wave, int r, int q) {
;     ...
;     if (wave >= 4) {
;         bf16x8 vf[2];
; #pragma unroll
;         for (int kk = 0; kk < 2; ++kk) vf[kk] = *(const bf16x8*)(VN + r * 72 + kk * 32 + q * 8);
; #pragma unroll
;         for (int t = 0; t < 2; ++t) { const int kb = (wave - 4) * 2 + t;
;             f32x4 a = Sacc[t] * S.gl;
; #pragma unroll
;             for (int kk = 0; kk < 2; ++kk) a = mfma16(S.f[t * 2 + kk], vf[kk], a);
;             Sacc[t] = a; const u32x2 ps = pk4(a);
;             *(u32x2*)(ST + r * 136 + kb * 16 + 4 * q) = ps;
;             if (ck + 1 < NCH) *(u32x2*)(dST + (((size_t)(ck + 1) * 8 + h) * 128 + vs * 16 + r) * 128 + kb * 16 + 4 * q) = ps; }
;     }
;     asm volatile("s_waitcnt lgkmcnt(0)" ::: "memory"); __builtin_amdgcn_s_barrier(); asm volatile("" ::: "memory");
.Ldq_B_loop:
	global_load_dwordx4 v[34:37], v10, s[14:15] offset:0
	global_load_dwordx4 v[38:41], v10, s[14:15] offset:64
	global_load_dwordx4 v[42:45], v10, s[14:15] offset:2048
	global_load_dwordx4 v[46:49], v10, s[14:15] offset:2112
	s_add_u32 s14, s14, 0x20000
	s_addc_u32 s15, s15, 0
	s_waitcnt vmcnt(20)
	v_readlane_b32 s40, v152, s41
	v_readlane_b32 s42, v153, s41
	s_cmp_lt_u32 s41, 64
	s_cselect_b32 s40, s40, s42
	s_add_u32 s41, s41, 1
	v_mul_f32_e32 v128, s40, v128
	v_mul_f32_e32 v129, s40, v129
	v_mul_f32_e32 v130, s40, v130
	v_mul_f32_e32 v131, s40, v131
	v_mul_f32_e32 v132, s40, v132
	v_mul_f32_e32 v133, s40, v133
	v_mul_f32_e32 v134, s40, v134
	v_mul_f32_e32 v135, s40, v135
	s_barrier
	ds_read_b128 v[144:147], v12
	ds_read_b128 v[148:151], v12 offset:64
	s_waitcnt lgkmcnt(1)
	v_mfma_f32_16x16x32_bf16 v[128:131], v[52:55], v[144:147], v[128:131]
	v_mfma_f32_16x16x32_bf16 v[132:135], v[60:63], v[144:147], v[132:135]
	s_waitcnt lgkmcnt(0)
	v_mfma_f32_16x16x32_bf16 v[128:131], v[56:59], v[148:151], v[128:131]
	v_mfma_f32_16x16x32_bf16 v[132:135], v[64:67], v[148:151], v[132:135]
	s_nop 7
	v_cvt_pk_bf16_f32 v136, v128, v129
	v_cvt_pk_bf16_f32 v137, v130, v131
	s_nop 1
	v_cvt_pk_bf16_f32 v138, v132, v133
	v_cvt_pk_bf16_f32 v139, v134, v135
	ds_write_b64 v13, v[136:137]
	ds_write_b64 v13, v[138:139] offset:32
	s_waitcnt lgkmcnt(0)
	s_barrier
	global_load_dwordx4 v[52:55], v10, s[14:15] offset:0
	global_load_dwordx4 v[56:59], v10, s[14:15] offset:64
	global_load_dwordx4 v[60:63], v10, s[14:15] offset:2048
	global_load_dwordx4 v[64:67], v10, s[14:15] offset:2112
	s_add_u32 s14, s14, 0x20000
	s_addc_u32 s15, s15, 0
	s_waitcnt vmcnt(20)
	v_readlane_b32 s40, v152, s41
	v_readlane_b32 s42, v153, s41
	s_cmp_lt_u32 s41, 64
	s_cselect_b32 s40, s40, s42
	s_add_u32 s41, s41, 1
	v_mul_f32_e32 v128, s40, v128
	v_mul_f32_e32 v129, s40, v129
	v_mul_f32_e32 v130, s40, v130
	v_mul_f32_e32 v131, s40, v131
	v_mul_f32_e32 v132, s40, v132
	v_mul_f32_e32 v133, s40, v133
	v_mul_f32_e32 v134, s40, v134
	v_mul_f32_e32 v135, s40, v135
	s_barrier
	ds_read_b128 v[144:147], v12
	ds_read_b128 v[148:151], v12 offset:64
	s_waitcnt lgkmcnt(1)
	v_mfma_f32_16x16x32_bf16 v[128:131], v[70:73], v[144:147], v[128:131]
	v_mfma_f32_16x16x32_bf16 v[132:135], v[78:81], v[144:147], v[132:135]
	s_waitcnt lgkmcnt(0)
	v_mfma_f32_16x16x32_bf16 v[128:131], v[74:77], v[148:151], v[128:131]
	v_mfma_f32_16x16x32_bf16 v[132:135], v[82:85], v[148:151], v[132:135]
	s_nop 7
	v_cvt_pk_bf16_f32 v136, v128, v129
	v_cvt_pk_bf16_f32 v137, v130, v131
	s_nop 1
	v_cvt_pk_bf16_f32 v138, v132, v133
	v_cvt_pk_bf16_f32 v139, v134, v135
	ds_write_b64 v13, v[136:137]
	ds_write_b64 v13, v[138:139] offset:32
	s_waitcnt lgkmcnt(0)
	s_barrier
	global_load_dwordx4 v[70:73], v10, s[14:15] offset:0
	global_load_dwordx4 v[74:77], v10, s[14:15] offset:64
	global_load_dwordx4 v[78:81], v10, s[14:15] offset:2048
	global_load_dwordx4 v[82:85], v10, s[14:15] offset:2112
	s_add_u32 s14, s14, 0x20000
	s_addc_u32 s15, s15, 0
	s_waitcnt vmcnt(20)
	v_readlane_b32 s40, v152, s41
	v_readlane_b32 s42, v153, s41
	s_cmp_lt_u32 s41, 64
	s_cselect_b32 s40, s40, s42
	s_add_u32 s41, s41, 1
	v_mul_f32_e32 v128, s40, v128
	v_mul_f32_e32 v129, s40, v129
	v_mul_f32_e32 v130, s40, v130
	v_mul_f32_e32 v131, s40, v131
	v_mul_f32_e32 v132, s40, v132
	v_mul_f32_e32 v133, s40, v133
	v_mul_f32_e32 v134, s40, v134
	v_mul_f32_e32 v135, s40, v135
	s_barrier
	ds_read_b128 v[144:147], v12
	ds_read_b128 v[148:151], v12 offset:64
	s_waitcnt lgkmcnt(1)
	v_mfma_f32_16x16x32_bf16 v[128:131], v[88:91], v[144:147], v[128:131]
	v_mfma_f32_16x16x32_bf16 v[132:135], v[96:99], v[144:147], v[132:135]
	s_waitcnt lgkmcnt(0)
	v_mfma_f32_16x16x32_bf16 v[128:131], v[92:95], v[148:151], v[128:131]
	v_mfma_f32_16x16x32_bf16 v[132:135], v[100:103], v[148:151], v[132:135]
	s_nop 7
	v_cvt_pk_bf16_f32 v136, v128, v129
	v_cvt_pk_bf16_f32 v137, v130, v131
	s_nop 1
	v_cvt_pk_bf16_f32 v138, v132, v133
	v_cvt_pk_bf16_f32 v139, v134, v135
	ds_write_b64 v13, v[136:137]
	ds_write_b64 v13, v[138:139] offset:32
	s_waitcnt lgkmcnt(0)
	s_barrier
	global_load_dwordx4 v[88:91], v10, s[14:15] offset:0
	global_load_dwordx4 v[92:95], v10, s[14:15] offset:64
	global_load_dwordx4 v[96:99], v10, s[14:15] offset:2048
	global_load_dwordx4 v[100:103], v10, s[14:15] offset:2112
	s_add_u32 s14, s14, 0x20000
	s_addc_u32 s15, s15, 0
	s_waitcnt vmcnt(20)
	v_readlane_b32 s40, v152, s41
	v_readlane_b32 s42, v153, s41
	s_cmp_lt_u32 s41, 64
	s_cselect_b32 s40, s40, s42
	s_add_u32 s41, s41, 1
	v_mul_f32_e32 v128, s40, v128
	v_mul_f32_e32 v129, s40, v129
	v_mul_f32_e32 v130, s40, v130
	v_mul_f32_e32 v131, s40, v131
	v_mul_f32_e32 v132, s40, v132
	v_mul_f32_e32 v133, s40, v133
	v_mul_f32_e32 v134, s40, v134
	v_mul_f32_e32 v135, s40, v135
	s_barrier
	ds_read_b128 v[144:147], v12
	ds_read_b128 v[148:151], v12 offset:64
	s_waitcnt lgkmcnt(1)
	v_mfma_f32_16x16x32_bf16 v[128:131], v[106:109], v[144:147], v[128:131]
	v_mfma_f32_16x16x32_bf16 v[132:135], v[114:117], v[144:147], v[132:135]
	s_waitcnt lgkmcnt(0)
	v_mfma_f32_16x16x32_bf16 v[128:131], v[110:113], v[148:151], v[128:131]
	v_mfma_f32_16x16x32_bf16 v[132:135], v[118:121], v[148:151], v[132:135]
	s_nop 7
	v_cvt_pk_bf16_f32 v136, v128, v129
	v_cvt_pk_bf16_f32 v137, v130, v131
	s_nop 1
	v_cvt_pk_bf16_f32 v138, v132, v133
	v_cvt_pk_bf16_f32 v139, v134, v135
	ds_write_b64 v13, v[136:137]
	ds_write_b64 v13, v[138:139] offset:32
	s_waitcnt lgkmcnt(0)
	s_barrier
; __device__ __forceinline__ u32x2 pk4(f32x4 v) { u32x2 r; r.x = pk2(v[0], v[1]); r.y = pk2(v[2], v[3]); return r; }
; __device__ __forceinline__ f32x4 mfma16(bf16x8 a, bf16x8 b, f32x4 c) { return __builtin_amdgcn_mfma_f32_16x16x32_bf16(a, b, c, 0, 0, 0); }
; __device__ __forceinline__ void dn_stage_load(DnStage& S, const bf16_t* dW, const bf16_t* dUT, const bf16_t* dKdT, const float* dGl, int ck, int h, int vs, int wave, int r, int q) {
;     ...
; #pragma unroll
;         for (int t = 0; t < 2; ++t)
; #pragma unroll
;             for (int kk = 0; kk < 2; ++kk) S.f[t * 2 + kk] = ldfrag(dKdT + (ch * 128 + ((wave - 4) * 2 + t) * 16 + r) * 64 + kk * 32 + q * 8);
;         S.gl = dGl[ch];
; __device__ __forceinline__ void dn_step(const DnStage& S, f32x4 (&Sacc)[2], bf16_t* ST, bf16_t* VN, bf16_t* dVnT, bf16_t* dST, int ck, int h, int vs, int wave, int r, int q) {
;     ...
;     if (wave >= 4) {
;         bf16x8 vf[2];
; #pragma unroll
;         for (int kk = 0; kk < 2; ++kk) vf[kk] = *(const bf16x8*)(VN + r * 72 + kk * 32 + q * 8);
; #pragma unroll
;         for (int t = 0; t < 2; ++t) { const int kb = (wave - 4) * 2 + t;
;             f32x4 a = Sacc[t] * S.gl;
; #pragma unroll
;             for (int kk = 0; kk < 2; ++kk) a = mfma16(S.f[t * 2 + kk], vf[kk], a);
;             Sacc[t] = a; const u32x2 ps = pk4(a);
;             *(u32x2*)(ST + r * 136 + kb * 16 + 4 * q) = ps;
;             if (ck + 1 < NCH) *(u32x2*)(dST + (((size_t)(ck + 1) * 8 + h) * 128 + vs * 16 + r) * 128 + kb * 16 + 4 * q) = ps; }
;     }
;     asm volatile("s_waitcnt lgkmcnt(0)" ::: "memory"); __builtin_amdgcn_s_barrier(); asm volatile("" ::: "memory");
	global_load_dwordx4 v[106:109], v10, s[14:15] offset:0
	global_load_dwordx4 v[110:113], v10, s[14:15] offset:64
	global_load_dwordx4 v[114:117], v10, s[14:15] offset:2048
	global_load_dwordx4 v[118:121], v10, s[14:15] offset:2112
	s_add_u32 s14, s14, 0x20000
	s_addc_u32 s15, s15, 0
	s_waitcnt vmcnt(20)
	v_readlane_b32 s40, v152, s41
	v_readlane_b32 s42, v153, s41
	s_cmp_lt_u32 s41, 64
	s_cselect_b32 s40, s40, s42
	s_add_u32 s41, s41, 1
	v_mul_f32_e32 v128, s40, v128
	v_mul_f32_e32 v129, s40, v129
	v_mul_f32_e32 v130, s40, v130
	v_mul_f32_e32 v131, s40, v131
	v_mul_f32_e32 v132, s40, v132
	v_mul_f32_e32 v133, s40, v133
	v_mul_f32_e32 v134, s40, v134
	v_mul_f32_e32 v135, s40, v135
	s_barrier
	ds_read_b128 v[144:147], v12
	ds_read_b128 v[148:151], v12 offset:64
	s_waitcnt lgkmcnt(1)
	v_mfma_f32_16x16x32_bf16 v[128:131], v[16:19], v[144:147], v[128:131]
	v_mfma_f32_16x16x32_bf16 v[132:135], v[24:27], v[144:147], v[132:135]
	s_waitcnt lgkmcnt(0)
	v_mfma_f32_16x16x32_bf16 v[128:131], v[20:23], v[148:151], v[128:131]
	v_mfma_f32_16x16x32_bf16 v[132:135], v[28:31], v[148:151], v[132:135]
	s_nop 7
	v_cvt_pk_bf16_f32 v136, v128, v129
	v_cvt_pk_bf16_f32 v137, v130, v131
	s_nop 1
	v_cvt_pk_bf16_f32 v138, v132, v133
	v_cvt_pk_bf16_f32 v139, v134, v135
	ds_write_b64 v13, v[136:137]
	ds_write_b64 v13, v[138:139] offset:32
	s_waitcnt lgkmcnt(0)
	s_barrier
	global_load_dwordx4 v[16:19], v10, s[14:15] offset:0
	global_load_dwordx4 v[20:23], v10, s[14:15] offset:64
	global_load_dwordx4 v[24:27], v10, s[14:15] offset:2048
	global_load_dwordx4 v[28:31], v10, s[14:15] offset:2112
	s_add_u32 s14, s14, 0x20000
	s_addc_u32 s15, s15, 0
	s_waitcnt vmcnt(20)
	v_readlane_b32 s40, v152, s41
	v_readlane_b32 s42, v153, s41
	s_cmp_lt_u32 s41, 64
	s_cselect_b32 s40, s40, s42
	s_add_u32 s41, s41, 1
	v_mul_f32_e32 v128, s40, v128
	v_mul_f32_e32 v129, s40, v129
	v_mul_f32_e32 v130, s40, v130
	v_mul_f32_e32 v131, s40, v131
	v_mul_f32_e32 v132, s40, v132
	v_mul_f32_e32 v133, s40, v133
	v_mul_f32_e32 v134, s40, v134
	v_mul_f32_e32 v135, s40, v135
	s_barrier
	ds_read_b128 v[144:147], v12
	ds_read_b128 v[148:151], v12 offset:64
	s_waitcnt lgkmcnt(1)
	v_mfma_f32_16x16x32_bf16 v[128:131], v[34:37], v[144:147], v[128:131]
	v_mfma_f32_16x16x32_bf16 v[132:135], v[42:45], v[144:147], v[132:135]
	s_waitcnt lgkmcnt(0)
	v_mfma_f32_16x16x32_bf16 v[128:131], v[38:41], v[148:151], v[128:131]
	v_mfma_f32_16x16x32_bf16 v[132:135], v[46:49], v[148:151], v[132:135]
	s_nop 7
	v_cvt_pk_bf16_f32 v136, v128, v129
	v_cvt_pk_bf16_f32 v137, v130, v131
	s_nop 1
	v_cvt_pk_bf16_f32 v138, v132, v133
	v_cvt_pk_bf16_f32 v139, v134, v135
	ds_write_b64 v13, v[136:137]
	ds_write_b64 v13, v[138:139] offset:32
	s_waitcnt lgkmcnt(0)
	s_barrier
	s_sub_u32 s20, s20, 1
	s_cmp_lg_u32 s20, 0
	s_cbranch_scc1 .Ldq_B_loop
	global_load_dwordx4 v[34:37], v10, s[14:15] offset:0
	global_load_dwordx4 v[38:41], v10, s[14:15] offset:64
	global_load_dwordx4 v[42:45], v10, s[14:15] offset:2048
	global_load_dwordx4 v[46:49], v10, s[14:15] offset:2112
	s_waitcnt vmcnt(20)
	v_readlane_b32 s40, v153, 58
	s_nop 1
	v_mul_f32_e32 v128, s40, v128
	v_mul_f32_e32 v129, s40, v129
	v_mul_f32_e32 v130, s40, v130
	v_mul_f32_e32 v131, s40, v131
	v_mul_f32_e32 v132, s40, v132
	v_mul_f32_e32 v133, s40, v133
	v_mul_f32_e32 v134, s40, v134
	v_mul_f32_e32 v135, s40, v135
	s_barrier
	ds_read_b128 v[144:147], v12
	ds_read_b128 v[148:151], v12 offset:64
	s_waitcnt lgkmcnt(1)
	v_mfma_f32_16x16x32_bf16 v[128:131], v[52:55], v[144:147], v[128:131]
	v_mfma_f32_16x16x32_bf16 v[132:135], v[60:63], v[144:147], v[132:135]
	s_waitcnt lgkmcnt(0)
	v_mfma_f32_16x16x32_bf16 v[128:131], v[56:59], v[148:151], v[128:131]
	v_mfma_f32_16x16x32_bf16 v[132:135], v[64:67], v[148:151], v[132:135]
	s_nop 7
	v_cvt_pk_bf16_f32 v136, v128, v129
	v_cvt_pk_bf16_f32 v137, v130, v131
	s_nop 1
	v_cvt_pk_bf16_f32 v138, v132, v133
	v_cvt_pk_bf16_f32 v139, v134, v135
	ds_write_b64 v13, v[136:137]
	ds_write_b64 v13, v[138:139] offset:32
	s_waitcnt lgkmcnt(0)
	s_barrier
	s_waitcnt vmcnt(16)
	v_readlane_b32 s40, v153, 59
	s_nop 1
	v_mul_f32_e32 v128, s40, v128
	v_mul_f32_e32 v129, s40, v129
	v_mul_f32_e32 v130, s40, v130
	v_mul_f32_e32 v131, s40, v131
	v_mul_f32_e32 v132, s40, v132
	v_mul_f32_e32 v133, s40, v133
	v_mul_f32_e32 v134, s40, v134
	v_mul_f32_e32 v135, s40, v135
	s_barrier
; __device__ __forceinline__ u32x2 pk4(f32x4 v) { u32x2 r; r.x = pk2(v[0], v[1]); r.y = pk2(v[2], v[3]); return r; }
; __device__ __forceinline__ f32x4 mfma16(bf16x8 a, bf16x8 b, f32x4 c) { return __builtin_amdgcn_mfma_f32_16x16x32_bf16(a, b, c, 0, 0, 0); }
; __device__ __forceinline__ void dn_stage_load(DnStage& S, const bf16_t* dW, const bf16_t* dUT, const bf16_t* dKdT, const float* dGl, int ck, int h, int vs, int wave, int r, int q) {
;     ...
; #pragma unroll
;         for (int t = 0; t < 2; ++t)
; #pragma unroll
;             for (int kk = 0; kk < 2; ++kk) S.f[t * 2 + kk] = ldfrag(dKdT + (ch * 128 + ((wave - 4) * 2 + t) * 16 + r) * 64 + kk * 32 + q * 8);
;         S.gl = dGl[ch];
; __device__ __forceinline__ void dn_step(const DnStage& S, f32x4 (&Sacc)[2], bf16_t* ST, bf16_t* VN, bf16_t* dVnT, bf16_t* dST, int ck, int h, int vs, int wave, int r, int q) {
;     ...
;     if (wave >= 4) {
;         bf16x8 vf[2];
; #pragma unroll
;         for (int kk = 0; kk < 2; ++kk) vf[kk] = *(const bf16x8*)(VN + r * 72 + kk * 32 + q * 8);
; #pragma unroll
;         for (int t = 0; t < 2; ++t) { const int kb = (wave - 4) * 2 + t;
;             f32x4 a = Sacc[t] * S.gl;
; #pragma unroll
;             for (int kk = 0; kk < 2; ++kk) a = mfma16(S.f[t * 2 + kk], vf[kk], a);
;             Sacc[t] = a; const u32x2 ps = pk4(a);
;             *(u32x2*)(ST + r * 136 + kb * 16 + 4 * q) = ps;
;             if (ck + 1 < NCH) *(u32x2*)(dST + (((size_t)(ck + 1) * 8 + h) * 128 + vs * 16 + r) * 128 + kb * 16 + 4 * q) = ps; }
;     }
;     asm volatile("s_waitcnt lgkmcnt(0)" ::: "memory"); __builtin_amdgcn_s_barrier(); asm volatile("" ::: "memory");
	ds_read_b128 v[144:147], v12
	ds_read_b128 v[148:151], v12 offset:64
	s_waitcnt lgkmcnt(1)
	v_mfma_f32_16x16x32_bf16 v[128:131], v[70:73], v[144:147], v[128:131]
	v_mfma_f32_16x16x32_bf16 v[132:135], v[78:81], v[144:147], v[132:135]
	s_waitcnt lgkmcnt(0)
	v_mfma_f32_16x16x32_bf16 v[128:131], v[74:77], v[148:151], v[128:131]
	v_mfma_f32_16x16x32_bf16 v[132:135], v[82:85], v[148:151], v[132:135]
	s_nop 7
	v_cvt_pk_bf16_f32 v136, v128, v129
	v_cvt_pk_bf16_f32 v137, v130, v131
	s_nop 1
	v_cvt_pk_bf16_f32 v138, v132, v133
	v_cvt_pk_bf16_f32 v139, v134, v135
	ds_write_b64 v13, v[136:137]
	ds_write_b64 v13, v[138:139] offset:32
	s_waitcnt lgkmcnt(0)
	s_barrier
	s_waitcnt vmcnt(12)
	v_readlane_b32 s40, v153, 60
	s_nop 1
	v_mul_f32_e32 v128, s40, v128
	v_mul_f32_e32 v129, s40, v129
	v_mul_f32_e32 v130, s40, v130
	v_mul_f32_e32 v131, s40, v131
	v_mul_f32_e32 v132, s40, v132
	v_mul_f32_e32 v133, s40, v133
	v_mul_f32_e32 v134, s40, v134
	v_mul_f32_e32 v135, s40, v135
	s_barrier
	ds_read_b128 v[144:147], v12
	ds_read_b128 v[148:151], v12 offset:64
	s_waitcnt lgkmcnt(1)
	v_mfma_f32_16x16x32_bf16 v[128:131], v[88:91], v[144:147], v[128:131]
	v_mfma_f32_16x16x32_bf16 v[132:135], v[96:99], v[144:147], v[132:135]
	s_waitcnt lgkmcnt(0)
	v_mfma_f32_16x16x32_bf16 v[128:131], v[92:95], v[148:151], v[128:131]
	v_mfma_f32_16x16x32_bf16 v[132:135], v[100:103], v[148:151], v[132:135]
	s_nop 7
	v_cvt_pk_bf16_f32 v136, v128, v129
	v_cvt_pk_bf16_f32 v137, v130, v131
	s_nop 1
	v_cvt_pk_bf16_f32 v138, v132, v133
	v_cvt_pk_bf16_f32 v139, v134, v135
	ds_write_b64 v13, v[136:137]
	ds_write_b64 v13, v[138:139] offset:32
	s_waitcnt lgkmcnt(0)
	s_barrier
	s_waitcnt vmcnt(8)
	v_readlane_b32 s40, v153, 61
	s_nop 1
	v_mul_f32_e32 v128, s40, v128
	v_mul_f32_e32 v129, s40, v129
	v_mul_f32_e32 v130, s40, v130
	v_mul_f32_e32 v131, s40, v131
	v_mul_f32_e32 v132, s40, v132
	v_mul_f32_e32 v133, s40, v133
	v_mul_f32_e32 v134, s40, v134
	v_mul_f32_e32 v135, s40, v135
	s_barrier
	ds_read_b128 v[144:147], v12
	ds_read_b128 v[148:151], v12 offset:64
	s_waitcnt lgkmcnt(1)
	v_mfma_f32_16x16x32_bf16 v[128:131], v[106:109], v[144:147], v[128:131]
	v_mfma_f32_16x16x32_bf16 v[132:135], v[114:117], v[144:147], v[132:135]
	s_waitcnt lgkmcnt(0)
	v_mfma_f32_16x16x32_bf16 v[128:131], v[110:113], v[148:151], v[128:131]
	v_mfma_f32_16x16x32_bf16 v[132:135], v[118:121], v[148:151], v[132:135]
	s_nop 7
	v_cvt_pk_bf16_f32 v136, v128, v129
	v_cvt_pk_bf16_f32 v137, v130, v131
	s_nop 1
	v_cvt_pk_bf16_f32 v138, v132, v133
	v_cvt_pk_bf16_f32 v139, v134, v135
	ds_write_b64 v13, v[136:137]
	ds_write_b64 v13, v[138:139] offset:32
	s_waitcnt lgkmcnt(0)
	s_barrier
	s_waitcnt vmcnt(4)
	v_readlane_b32 s40, v153, 62
	s_nop 1
	v_mul_f32_e32 v128, s40, v128
	v_mul_f32_e32 v129, s40, v129
	v_mul_f32_e32 v130, s40, v130
	v_mul_f32_e32 v131, s40, v131
	v_mul_f32_e32 v132, s40, v132
	v_mul_f32_e32 v133, s40, v133
	v_mul_f32_e32 v134, s40, v134
	v_mul_f32_e32 v135, s40, v135
	s_barrier
	ds_read_b128 v[144:147], v12
	ds_read_b128 v[148:151], v12 offset:64
	s_waitcnt lgkmcnt(1)
	v_mfma_f32_16x16x32_bf16 v[128:131], v[16:19], v[144:147], v[128:131]
	v_mfma_f32_16x16x32_bf16 v[132:135], v[24:27], v[144:147], v[132:135]
	s_waitcnt lgkmcnt(0)
	v_mfma_f32_16x16x32_bf16 v[128:131], v[20:23], v[148:151], v[128:131]
	v_mfma_f32_16x16x32_bf16 v[132:135], v[28:31], v[148:151], v[132:135]
	s_nop 7
	v_cvt_pk_bf16_f32 v136, v128, v129
	v_cvt_pk_bf16_f32 v137, v130, v131
	s_nop 1
	v_cvt_pk_bf16_f32 v138, v132, v133
	v_cvt_pk_bf16_f32 v139, v134, v135
	ds_write_b64 v13, v[136:137]
	ds_write_b64 v13, v[138:139] offset:32
	s_waitcnt lgkmcnt(0)
	s_barrier
	s_waitcnt vmcnt(0)
	v_readlane_b32 s40, v153, 63
	s_nop 1
	v_mul_f32_e32 v128, s40, v128
	v_mul_f32_e32 v129, s40, v129
	v_mul_f32_e32 v130, s40, v130
	v_mul_f32_e32 v131, s40, v131
	v_mul_f32_e32 v132, s40, v132
	v_mul_f32_e32 v133, s40, v133
	v_mul_f32_e32 v134, s40, v134
	v_mul_f32_e32 v135, s40, v135
	s_barrier
	ds_read_b128 v[144:147], v12
	ds_read_b128 v[148:151], v12 offset:64
	s_waitcnt lgkmcnt(1)
	v_mfma_f32_16x16x32_bf16 v[128:131], v[34:37], v[144:147], v[128:131]
	v_mfma_f32_16x16x32_bf16 v[132:135], v[42:45], v[144:147], v[132:135]
	s_waitcnt lgkmcnt(0)
	v_mfma_f32_16x16x32_bf16 v[128:131], v[38:41], v[148:151], v[128:131]
	v_mfma_f32_16x16x32_bf16 v[132:135], v[46:49], v[148:151], v[132:135]
	s_nop 7
	v_cvt_pk_bf16_f32 v136, v128, v129
	v_cvt_pk_bf16_f32 v137, v130, v131
	s_nop 1
	v_cvt_pk_bf16_f32 v138, v132, v133
	v_cvt_pk_bf16_f32 v139, v134, v135
	ds_write_b64 v13, v[136:137]
	ds_write_b64 v13, v[138:139] offset:32
	s_waitcnt lgkmcnt(0)
	s_barrier
